# peeled first K-loop iteration in all four GEMM copies: first MFMA per accumulator takes srcC=0, the 128 per-unit accumulator clears are gone (plus no per-segment setprio, trimmed waits, saddr LDS-DMA,
# speedup vs baseline: 1.0111x; 1.0043x over previous
; #define PG8_STAGE(bufoff, gbase, voff) do { _Pragma("unroll") for (int _i = 0; _i < 2; ++_i) \
;         __builtin_amdgcn_global_load_lds((const unsigned*)((const char*)(gbase) + (voff)[_i]), (PG8_LAS unsigned*)(lds + (bufoff) + ldsw + _i * 8192), 16, 0, 0); } while (0)
; #define PG8_LDA(dst, b, h) do { _Pragma("unroll") for (int m = 0; m < 4; ++m) _Pragma("unroll") for (int k = 0; k < 2; ++k) dst[m][k] = *(const PG8_LAS bf16x8*)(lds + PG8_SA(b, h) + aoff + m * 2048 + k * 1024); } while (0)
; #define PG8_LDB(dst, b, h) do { _Pragma("unroll") for (int n = 0; n < 2; ++n) _Pragma("unroll") for (int k = 0; k < 2; ++k) dst[n][k] = *(const PG8_LAS bf16x8*)(lds + PG8_SB(b, h) + boff + n * 2048 + k * 1024); } while (0)
; #define PG8_MMA(ai, bj, At, Bt) do { __builtin_amdgcn_s_setprio(1); _Pragma("unroll") for (int m = 0; m < 4; ++m) _Pragma("unroll") for (int n = 0; n < 2; ++n) _Pragma("unroll") for (int k = 0; k < 2; ++k) \
;         acc[ai][bj][m][n] = __builtin_amdgcn_mfma_f32_16x16x32_bf16(Bt[n][k], At[m][k], acc[ai][bj][m][n], 0, 0, 0); __builtin_amdgcn_s_setprio(0); } while (0)
; #define PG8_BAR __builtin_amdgcn_s_barrier()
; template <class Epi, class Sched, bool ALIGN_EPI = false, bool SP2 = false>
; __device__ __forceinline__ void gemm_phase(PG8_LAS unsigned char* lds, const Gemm g, const Sched& S, const Epi& E) {
;     ...
;         const bool has_next = S.next(ui + 1, nxt);
;         const char* nA = has_next ? (const char*)g.A + (size_t)nxt.pm * tstep : cA; const char* nB = has_next ? (const char*)g.Bt + (size_t)nxt.pn * tstep : cB;
;         for (int t = 0; t < nt; t += 2) {
;             const bool last = (t == nt - 2);
;             const char* a1 = cA + (size_t)(t + 1) * kstep;
;             const char* a2 = last ? nA : cA + (size_t)(t + 2) * kstep; const char* b2 = last ? nB : cB + (size_t)(t + 2) * kstep;
;             const char* a3 = a2 + kstep; const char* b3 = b2 + kstep;
;             if (last && has_next) S.a_ready(nxt);
;             if constexpr (SP2) {
;             PG8_LDB(B0, 0, 0); PG8_LDB(B1, 0, 1); PG8_SCHED; PG8_LDA(At, 0, 0); PG8_STAGE(PG8_SA(1, 1), a1 + hstep, voffA);
;             PG8_WAIT_V(8); PG8_WAIT_L(0); PG8_BAR; PG8_MMA(0, 0, At, B0); PG8_MMA(0, 1, At, B1); PG8_BAR; PG8_SCHED;
;             PG8_LDA(At, 0, 1); PG8_STAGE(PG8_SB(0, 0), b2, voffB); PG8_STAGE(PG8_SB(0, 1), b2 + hstep, voffB); PG8_STAGE(PG8_SA(0, 0), a2, voffA);
.LBB0_64:
	s_ashr_i32 s11, s10, 31
	s_lshl_b64 s[12:13], s[10:11], 19
	s_add_u32 s12, s66, s12
	s_addc_u32 s13, s67, s13
	s_and_b64 s[14:15], s[42:43], exec
	s_cselect_b32 s11, s13, s19
	s_cselect_b32 s45, s12, s18
	s_ashr_i32 s9, s8, 31
	s_lshl_b64 s[14:15], s[8:9], 19
	s_add_u32 s14, s28, s14
	s_addc_u32 s15, s29, s15
	s_and_b64 s[22:23], s[42:43], exec
	s_cselect_b32 s9, s15, s21
	s_cselect_b32 s46, s14, s20
	s_add_u32 s18, s18, 0x40080
	s_addc_u32 s19, s19, 0
	s_add_u32 s47, s20, 0x100
	s_addc_u32 s48, s21, 0
	s_mov_b32 s49, -2
	s_mov_b64 s[54:55], 0x80
	v_add_u32_e32 v216, 0x10000, v141
	s_add_u32 s20, s18, 0xfffc0080
	s_addc_u32 s21, s19, -1
	s_cmp_eq_u32 s49, 12
	s_cselect_b32 s23, s11, s21
	s_cselect_b32 s22, s45, s20
	s_cselect_b32 s21, s9, s48
	s_cselect_b32 s20, s46, s47
	ds_read_b128 v[146:149], v216
	ds_read_b128 v[150:153], v216 offset:1024
	ds_read_b128 v[154:157], v216 offset:2048
	ds_read_b128 v[158:161], v216 offset:3072
	ds_read_b128 v[162:165], v216 offset:16384
	ds_read_b128 v[166:169], v216 offset:17408
	ds_read_b128 v[170:173], v216 offset:18432
	ds_read_b128 v[174:177], v216 offset:19456
	s_add_i32 m0, s34, 0xc000
	ds_read_b128 v[178:181], v144
	ds_read_b128 v[188:191], v144 offset:1024
	ds_read_b128 v[192:195], v144 offset:2048
	ds_read_b128 v[196:199], v144 offset:3072
	ds_read_b128 v[200:203], v144 offset:4096
	ds_read_b128 v[204:207], v144 offset:5120
	ds_read_b128 v[208:211], v144 offset:6144
	ds_read_b128 v[212:215], v144 offset:7168
	global_load_lds_dwordx4 v136, s[18:19]
	s_add_i32 m0, s34, 0xe000
	s_add_i32 s50, s33, 0x10000
	global_load_lds_dwordx4 v138, s[18:19]
	s_waitcnt vmcnt(8)
	s_waitcnt lgkmcnt(0)
	s_barrier
	v_mfma_f32_16x16x32_bf16 v[126:129], v[146:149], v[178:181], 0
	v_mfma_f32_16x16x32_bf16 v[118:121], v[154:157], v[178:181], 0
	v_mfma_f32_16x16x32_bf16 v[110:113], v[146:149], v[192:195], 0
	v_mfma_f32_16x16x32_bf16 v[102:105], v[154:157], v[192:195], 0
	v_mfma_f32_16x16x32_bf16 v[94:97], v[146:149], v[200:203], 0
	v_mfma_f32_16x16x32_bf16 v[86:89], v[154:157], v[200:203], 0
	v_mfma_f32_16x16x32_bf16 v[78:81], v[146:149], v[208:211], 0
	v_mfma_f32_16x16x32_bf16 v[70:73], v[154:157], v[208:211], 0
	v_mfma_f32_16x16x32_bf16 v[126:129], v[150:153], v[188:191], v[126:129]
	v_mfma_f32_16x16x32_bf16 v[118:121], v[158:161], v[188:191], v[118:121]
	v_mfma_f32_16x16x32_bf16 v[110:113], v[150:153], v[196:199], v[110:113]
	v_mfma_f32_16x16x32_bf16 v[102:105], v[158:161], v[196:199], v[102:105]
	v_mfma_f32_16x16x32_bf16 v[94:97], v[150:153], v[204:207], v[94:97]
	v_mfma_f32_16x16x32_bf16 v[86:89], v[158:161], v[204:207], v[86:89]
	v_mfma_f32_16x16x32_bf16 v[78:81], v[150:153], v[212:215], v[78:81]
	v_mfma_f32_16x16x32_bf16 v[70:73], v[158:161], v[212:215], v[70:73]
	v_mfma_f32_16x16x32_bf16 v[122:125], v[162:165], v[178:181], 0
	v_mfma_f32_16x16x32_bf16 v[114:117], v[170:173], v[178:181], 0
	v_mfma_f32_16x16x32_bf16 v[106:109], v[162:165], v[192:195], 0
	v_mfma_f32_16x16x32_bf16 v[98:101], v[170:173], v[192:195], 0
	v_mfma_f32_16x16x32_bf16 v[90:93], v[162:165], v[200:203], 0
	v_mfma_f32_16x16x32_bf16 v[82:85], v[170:173], v[200:203], 0
	v_mfma_f32_16x16x32_bf16 v[74:77], v[162:165], v[208:211], 0
	v_mfma_f32_16x16x32_bf16 v[66:69], v[170:173], v[208:211], 0
	v_mfma_f32_16x16x32_bf16 v[122:125], v[166:169], v[188:191], v[122:125]
	v_mfma_f32_16x16x32_bf16 v[114:117], v[174:177], v[188:191], v[114:117]
	v_mfma_f32_16x16x32_bf16 v[106:109], v[166:169], v[196:199], v[106:109]
	v_mfma_f32_16x16x32_bf16 v[98:101], v[174:177], v[196:199], v[98:101]
	v_mfma_f32_16x16x32_bf16 v[90:93], v[166:169], v[204:207], v[90:93]
	v_mfma_f32_16x16x32_bf16 v[82:85], v[174:177], v[204:207], v[82:85]
	v_mfma_f32_16x16x32_bf16 v[74:77], v[166:169], v[212:215], v[74:77]
	v_mfma_f32_16x16x32_bf16 v[66:69], v[174:177], v[212:215], v[66:69]
	s_barrier
	s_mov_b32 m0, s50
	ds_read_b128 v[178:181], v144 offset:16384
	ds_read_b128 v[188:191], v144 offset:17408
	ds_read_b128 v[192:195], v144 offset:18432
	ds_read_b128 v[196:199], v144 offset:19456
	ds_read_b128 v[200:203], v144 offset:20480
	ds_read_b128 v[204:207], v144 offset:21504
	ds_read_b128 v[208:211], v144 offset:22528
	ds_read_b128 v[212:215], v144 offset:23552
	global_load_lds_dwordx4 v64, s[20:21]
	s_add_i32 m0, s50, 0x2000
	s_add_u32 s98, s20, 0x40000
	s_addc_u32 s99, s21, 0
	global_load_lds_dwordx4 v130, s[20:21]
	s_add_i32 m0, s33, 0x14000
	s_nop 0
	global_load_lds_dwordx4 v64, s[98:99]
	s_add_i32 m0, s33, 0x16000
	s_nop 0
	global_load_lds_dwordx4 v130, s[98:99]
	s_mov_b32 m0, s34
	s_nop 0
	global_load_lds_dwordx4 v134, s[22:23]
	s_mov_b32 m0, s35
	s_nop 0
	global_load_lds_dwordx4 v132, s[22:23]
	s_waitcnt vmcnt(8)
	s_waitcnt lgkmcnt(0)
	s_barrier
; #define PG8_STAGE(bufoff, gbase, voff) do { _Pragma("unroll") for (int _i = 0; _i < 2; ++_i) \
;         __builtin_amdgcn_global_load_lds((const unsigned*)((const char*)(gbase) + (voff)[_i]), (PG8_LAS unsigned*)(lds + (bufoff) + ldsw + _i * 8192), 16, 0, 0); } while (0)
; #define PG8_LDA(dst, b, h) do { _Pragma("unroll") for (int m = 0; m < 4; ++m) _Pragma("unroll") for (int k = 0; k < 2; ++k) dst[m][k] = *(const PG8_LAS bf16x8*)(lds + PG8_SA(b, h) + aoff + m * 2048 + k * 1024); } while (0)
; #define PG8_LDB(dst, b, h) do { _Pragma("unroll") for (int n = 0; n < 2; ++n) _Pragma("unroll") for (int k = 0; k < 2; ++k) dst[n][k] = *(const PG8_LAS bf16x8*)(lds + PG8_SB(b, h) + boff + n * 2048 + k * 1024); } while (0)
; #define PG8_MMA(ai, bj, At, Bt) do { __builtin_amdgcn_s_setprio(1); _Pragma("unroll") for (int m = 0; m < 4; ++m) _Pragma("unroll") for (int n = 0; n < 2; ++n) _Pragma("unroll") for (int k = 0; k < 2; ++k) \
;         acc[ai][bj][m][n] = __builtin_amdgcn_mfma_f32_16x16x32_bf16(Bt[n][k], At[m][k], acc[ai][bj][m][n], 0, 0, 0); __builtin_amdgcn_s_setprio(0); } while (0)
; #define PG8_WAIT_V(n) asm volatile("s_waitcnt vmcnt(" #n ")" ::: "memory")
; #define PG8_WAIT_L(n) asm volatile("s_waitcnt lgkmcnt(" #n ")" ::: "memory")
; #define PG8_BAR __builtin_amdgcn_s_barrier()
; #define PG8_SCHED __builtin_amdgcn_sched_barrier(0)
; template <class Epi, class Sched, bool ALIGN_EPI = false, bool SP2 = false>
; __device__ __forceinline__ void gemm_phase(PG8_LAS unsigned char* lds, const Gemm g, const Sched& S, const Epi& E) {
;     ...
;             PG8_WAIT_V(8); PG8_WAIT_L(0); PG8_BAR; PG8_MMA(1, 0, At, B0); PG8_MMA(1, 1, At, B1); PG8_BAR; PG8_SCHED;
;             PG8_LDB(B0, 1, 0); PG8_LDB(B1, 1, 1); PG8_SCHED; PG8_LDA(At, 1, 0); PG8_STAGE(PG8_SA(0, 1), a2 + hstep, voffA);
;             PG8_WAIT_V(8); PG8_WAIT_L(0); PG8_BAR; PG8_MMA(0, 0, At, B0); PG8_MMA(0, 1, At, B1); PG8_BAR; PG8_SCHED;
	v_mfma_f32_16x16x32_bf16 v[60:63], v[146:149], v[178:181], 0
	v_mfma_f32_16x16x32_bf16 v[52:55], v[154:157], v[178:181], 0
	v_mfma_f32_16x16x32_bf16 v[44:47], v[146:149], v[192:195], 0
	v_mfma_f32_16x16x32_bf16 v[36:39], v[154:157], v[192:195], 0
	v_mfma_f32_16x16x32_bf16 v[28:31], v[146:149], v[200:203], 0
	v_mfma_f32_16x16x32_bf16 v[20:23], v[154:157], v[200:203], 0
	v_mfma_f32_16x16x32_bf16 v[12:15], v[146:149], v[208:211], 0
	v_mfma_f32_16x16x32_bf16 v[4:7], v[154:157], v[208:211], 0
	v_mfma_f32_16x16x32_bf16 v[60:63], v[150:153], v[188:191], v[60:63]
	v_mfma_f32_16x16x32_bf16 v[52:55], v[158:161], v[188:191], v[52:55]
	v_mfma_f32_16x16x32_bf16 v[44:47], v[150:153], v[196:199], v[44:47]
	v_mfma_f32_16x16x32_bf16 v[36:39], v[158:161], v[196:199], v[36:39]
	v_mfma_f32_16x16x32_bf16 v[28:31], v[150:153], v[204:207], v[28:31]
	v_mfma_f32_16x16x32_bf16 v[20:23], v[158:161], v[204:207], v[20:23]
	v_mfma_f32_16x16x32_bf16 v[12:15], v[150:153], v[212:215], v[12:15]
	v_mfma_f32_16x16x32_bf16 v[4:7], v[158:161], v[212:215], v[4:7]
	v_mfma_f32_16x16x32_bf16 v[56:59], v[162:165], v[178:181], 0
	v_mfma_f32_16x16x32_bf16 v[48:51], v[170:173], v[178:181], 0
	v_mfma_f32_16x16x32_bf16 v[40:43], v[162:165], v[192:195], 0
	v_mfma_f32_16x16x32_bf16 v[32:35], v[170:173], v[192:195], 0
	v_mfma_f32_16x16x32_bf16 v[24:27], v[162:165], v[200:203], 0
	v_mfma_f32_16x16x32_bf16 v[16:19], v[170:173], v[200:203], 0
	v_mfma_f32_16x16x32_bf16 v[8:11], v[162:165], v[208:211], 0
	v_mfma_f32_16x16x32_bf16 v[0:3], v[170:173], v[208:211], 0
	v_mfma_f32_16x16x32_bf16 v[56:59], v[166:169], v[188:191], v[56:59]
	v_mfma_f32_16x16x32_bf16 v[48:51], v[174:177], v[188:191], v[48:51]
	v_mfma_f32_16x16x32_bf16 v[40:43], v[166:169], v[196:199], v[40:43]
	v_mfma_f32_16x16x32_bf16 v[32:35], v[174:177], v[196:199], v[32:35]
	v_mfma_f32_16x16x32_bf16 v[24:27], v[166:169], v[204:207], v[24:27]
	v_mfma_f32_16x16x32_bf16 v[16:19], v[174:177], v[204:207], v[16:19]
	v_mfma_f32_16x16x32_bf16 v[8:11], v[166:169], v[212:215], v[8:11]
	v_mfma_f32_16x16x32_bf16 v[0:3], v[174:177], v[212:215], v[0:3]
	s_barrier
	ds_read_b128 v[146:149], v216 offset:32768
	ds_read_b128 v[150:153], v216 offset:33792
	ds_read_b128 v[154:157], v216 offset:34816
	ds_read_b128 v[158:161], v216 offset:35840
	ds_read_b128 v[162:165], v216 offset:49152
	ds_read_b128 v[166:169], v216 offset:50176
	ds_read_b128 v[170:173], v216 offset:51200
	ds_read_b128 v[174:177], v216 offset:52224
	s_add_u32 s22, s22, 0x40000
	s_addc_u32 s23, s23, 0
	s_mov_b32 m0, s36
	ds_read_b128 v[178:181], v144 offset:32768
	ds_read_b128 v[188:191], v144 offset:33792
	ds_read_b128 v[192:195], v144 offset:34816
	ds_read_b128 v[196:199], v144 offset:35840
	ds_read_b128 v[200:203], v144 offset:36864
	ds_read_b128 v[204:207], v144 offset:37888
	ds_read_b128 v[208:211], v144 offset:38912
	ds_read_b128 v[212:215], v144 offset:39936
	global_load_lds_dwordx4 v134, s[22:23]
	s_mov_b32 m0, s37
	s_add_u32 s98, s20, 0x80
	s_addc_u32 s99, s21, 0
	global_load_lds_dwordx4 v132, s[22:23]
	s_waitcnt vmcnt(8)
	s_waitcnt lgkmcnt(0)
	s_barrier
	v_mfma_f32_16x16x32_bf16 v[126:129], v[146:149], v[178:181], v[126:129]
	v_mfma_f32_16x16x32_bf16 v[118:121], v[154:157], v[178:181], v[118:121]
	v_mfma_f32_16x16x32_bf16 v[110:113], v[146:149], v[192:195], v[110:113]
	v_mfma_f32_16x16x32_bf16 v[102:105], v[154:157], v[192:195], v[102:105]
	v_mfma_f32_16x16x32_bf16 v[94:97], v[146:149], v[200:203], v[94:97]
	v_mfma_f32_16x16x32_bf16 v[86:89], v[154:157], v[200:203], v[86:89]
	v_mfma_f32_16x16x32_bf16 v[78:81], v[146:149], v[208:211], v[78:81]
	v_mfma_f32_16x16x32_bf16 v[70:73], v[154:157], v[208:211], v[70:73]
	v_mfma_f32_16x16x32_bf16 v[126:129], v[150:153], v[188:191], v[126:129]
	v_mfma_f32_16x16x32_bf16 v[118:121], v[158:161], v[188:191], v[118:121]
	v_mfma_f32_16x16x32_bf16 v[110:113], v[150:153], v[196:199], v[110:113]
	v_mfma_f32_16x16x32_bf16 v[102:105], v[158:161], v[196:199], v[102:105]
	v_mfma_f32_16x16x32_bf16 v[94:97], v[150:153], v[204:207], v[94:97]
	v_mfma_f32_16x16x32_bf16 v[86:89], v[158:161], v[204:207], v[86:89]
	v_mfma_f32_16x16x32_bf16 v[78:81], v[150:153], v[212:215], v[78:81]
	v_mfma_f32_16x16x32_bf16 v[70:73], v[158:161], v[212:215], v[70:73]
	v_mfma_f32_16x16x32_bf16 v[122:125], v[162:165], v[178:181], v[122:125]
	v_mfma_f32_16x16x32_bf16 v[114:117], v[170:173], v[178:181], v[114:117]
	v_mfma_f32_16x16x32_bf16 v[106:109], v[162:165], v[192:195], v[106:109]
	v_mfma_f32_16x16x32_bf16 v[98:101], v[170:173], v[192:195], v[98:101]
	v_mfma_f32_16x16x32_bf16 v[90:93], v[162:165], v[200:203], v[90:93]
	v_mfma_f32_16x16x32_bf16 v[82:85], v[170:173], v[200:203], v[82:85]
	v_mfma_f32_16x16x32_bf16 v[74:77], v[162:165], v[208:211], v[74:77]
	v_mfma_f32_16x16x32_bf16 v[66:69], v[170:173], v[208:211], v[66:69]
	v_mfma_f32_16x16x32_bf16 v[122:125], v[166:169], v[188:191], v[122:125]
	v_mfma_f32_16x16x32_bf16 v[114:117], v[174:177], v[188:191], v[114:117]
	v_mfma_f32_16x16x32_bf16 v[106:109], v[166:169], v[196:199], v[106:109]
	v_mfma_f32_16x16x32_bf16 v[98:101], v[174:177], v[196:199], v[98:101]
	v_mfma_f32_16x16x32_bf16 v[90:93], v[166:169], v[204:207], v[90:93]
	v_mfma_f32_16x16x32_bf16 v[82:85], v[174:177], v[204:207], v[82:85]
	v_mfma_f32_16x16x32_bf16 v[74:77], v[166:169], v[212:215], v[74:77]
	v_mfma_f32_16x16x32_bf16 v[66:69], v[174:177], v[212:215], v[66:69]
	s_barrier
; #define PG8_STAGE(bufoff, gbase, voff) do { _Pragma("unroll") for (int _i = 0; _i < 2; ++_i) \
;         __builtin_amdgcn_global_load_lds((const unsigned*)((const char*)(gbase) + (voff)[_i]), (PG8_LAS unsigned*)(lds + (bufoff) + ldsw + _i * 8192), 16, 0, 0); } while (0)
; #define PG8_LDA(dst, b, h) do { _Pragma("unroll") for (int m = 0; m < 4; ++m) _Pragma("unroll") for (int k = 0; k < 2; ++k) dst[m][k] = *(const PG8_LAS bf16x8*)(lds + PG8_SA(b, h) + aoff + m * 2048 + k * 1024); } while (0)
; #define PG8_MMA(ai, bj, At, Bt) do { __builtin_amdgcn_s_setprio(1); _Pragma("unroll") for (int m = 0; m < 4; ++m) _Pragma("unroll") for (int n = 0; n < 2; ++n) _Pragma("unroll") for (int k = 0; k < 2; ++k) \
;         acc[ai][bj][m][n] = __builtin_amdgcn_mfma_f32_16x16x32_bf16(Bt[n][k], At[m][k], acc[ai][bj][m][n], 0, 0, 0); __builtin_amdgcn_s_setprio(0); } while (0)
; #define PG8_WAIT_V(n) asm volatile("s_waitcnt vmcnt(" #n ")" ::: "memory")
; #define PG8_WAIT_L(n) asm volatile("s_waitcnt lgkmcnt(" #n ")" ::: "memory")
; #define PG8_BAR __builtin_amdgcn_s_barrier()
; #define PG8_SCHED __builtin_amdgcn_sched_barrier(0)
; template <class Epi, class Sched, bool ALIGN_EPI = false, bool SP2 = false>
; __device__ __forceinline__ void gemm_phase(PG8_LAS unsigned char* lds, const Gemm g, const Sched& S, const Epi& E) {
;     ...
;             PG8_LDA(At, 1, 1); PG8_STAGE(PG8_SB(1, 0), b3, voffB); PG8_STAGE(PG8_SB(1, 1), b3 + hstep, voffB); PG8_STAGE(PG8_SA(1, 0), a3, voffA);
;             PG8_WAIT_V(8); PG8_WAIT_L(0); PG8_BAR; PG8_MMA(1, 0, At, B0); PG8_MMA(1, 1, At, B1); PG8_BAR; PG8_SCHED;
	s_add_i32 m0, s33, 0x18000
	ds_read_b128 v[178:181], v144 offset:49152
	ds_read_b128 v[188:191], v144 offset:50176
	ds_read_b128 v[192:195], v144 offset:51200
	ds_read_b128 v[196:199], v144 offset:52224
	ds_read_b128 v[200:203], v144 offset:53248
	ds_read_b128 v[204:207], v144 offset:54272
	ds_read_b128 v[208:211], v144 offset:55296
	ds_read_b128 v[212:215], v144 offset:56320
	global_load_lds_dwordx4 v64, s[98:99]
	s_add_i32 m0, s33, 0x1a000
	s_add_u32 s20, s20, 0x40080
	s_addc_u32 s21, s21, 0
	global_load_lds_dwordx4 v130, s[98:99]
	s_add_i32 m0, s33, 0x1c000
	s_add_u32 s22, s22, 0xfffc0080
	s_addc_u32 s23, s23, -1
	global_load_lds_dwordx4 v64, s[20:21]
	s_add_i32 m0, s33, 0x1e000
	s_nop 0
	global_load_lds_dwordx4 v130, s[20:21]
	s_mov_b32 m0, s38
	s_nop 0
	global_load_lds_dwordx4 v134, s[22:23]
	s_mov_b32 m0, s39
	s_nop 0
	global_load_lds_dwordx4 v132, s[22:23]
	s_waitcnt vmcnt(8)
	s_waitcnt lgkmcnt(0)
	s_barrier
	v_mfma_f32_16x16x32_bf16 v[60:63], v[146:149], v[178:181], v[60:63]
	v_mfma_f32_16x16x32_bf16 v[52:55], v[154:157], v[178:181], v[52:55]
	v_mfma_f32_16x16x32_bf16 v[44:47], v[146:149], v[192:195], v[44:47]
	v_mfma_f32_16x16x32_bf16 v[36:39], v[154:157], v[192:195], v[36:39]
	v_mfma_f32_16x16x32_bf16 v[28:31], v[146:149], v[200:203], v[28:31]
	v_mfma_f32_16x16x32_bf16 v[20:23], v[154:157], v[200:203], v[20:23]
	v_mfma_f32_16x16x32_bf16 v[12:15], v[146:149], v[208:211], v[12:15]
	v_mfma_f32_16x16x32_bf16 v[4:7], v[154:157], v[208:211], v[4:7]
	v_mfma_f32_16x16x32_bf16 v[60:63], v[150:153], v[188:191], v[60:63]
	v_mfma_f32_16x16x32_bf16 v[52:55], v[158:161], v[188:191], v[52:55]
	v_mfma_f32_16x16x32_bf16 v[44:47], v[150:153], v[196:199], v[44:47]
	v_mfma_f32_16x16x32_bf16 v[36:39], v[158:161], v[196:199], v[36:39]
	v_mfma_f32_16x16x32_bf16 v[28:31], v[150:153], v[204:207], v[28:31]
	v_mfma_f32_16x16x32_bf16 v[20:23], v[158:161], v[204:207], v[20:23]
	v_mfma_f32_16x16x32_bf16 v[12:15], v[150:153], v[212:215], v[12:15]
	v_mfma_f32_16x16x32_bf16 v[4:7], v[158:161], v[212:215], v[4:7]
	v_mfma_f32_16x16x32_bf16 v[56:59], v[162:165], v[178:181], v[56:59]
	v_mfma_f32_16x16x32_bf16 v[48:51], v[170:173], v[178:181], v[48:51]
	v_mfma_f32_16x16x32_bf16 v[40:43], v[162:165], v[192:195], v[40:43]
	v_mfma_f32_16x16x32_bf16 v[32:35], v[170:173], v[192:195], v[32:35]
	v_mfma_f32_16x16x32_bf16 v[24:27], v[162:165], v[200:203], v[24:27]
	v_mfma_f32_16x16x32_bf16 v[16:19], v[170:173], v[200:203], v[16:19]
	v_mfma_f32_16x16x32_bf16 v[8:11], v[162:165], v[208:211], v[8:11]
	v_mfma_f32_16x16x32_bf16 v[0:3], v[170:173], v[208:211], v[0:3]
	v_mfma_f32_16x16x32_bf16 v[56:59], v[166:169], v[188:191], v[56:59]
	v_mfma_f32_16x16x32_bf16 v[48:51], v[174:177], v[188:191], v[48:51]
	v_mfma_f32_16x16x32_bf16 v[40:43], v[166:169], v[196:199], v[40:43]
	v_mfma_f32_16x16x32_bf16 v[32:35], v[174:177], v[196:199], v[32:35]
	v_mfma_f32_16x16x32_bf16 v[24:27], v[166:169], v[204:207], v[24:27]
	v_mfma_f32_16x16x32_bf16 v[16:19], v[174:177], v[204:207], v[16:19]
	v_mfma_f32_16x16x32_bf16 v[8:11], v[166:169], v[212:215], v[8:11]
	v_mfma_f32_16x16x32_bf16 v[0:3], v[174:177], v[212:215], v[0:3]
	s_barrier
	s_add_i32 s49, s49, 2
	s_add_u32 s18, s18, 0x100
	s_addc_u32 s19, s19, 0
	s_add_u32 s47, s47, 0x100
	s_addc_u32 s48, s48, 0
	s_cmp_gt_u32 s49, 13

; #define PG8_STAGE(bufoff, gbase, voff) do { _Pragma("unroll") for (int _i = 0; _i < 2; ++_i) \
;         __builtin_amdgcn_global_load_lds((const unsigned*)((const char*)(gbase) + (voff)[_i]), (PG8_LAS unsigned*)(lds + (bufoff) + ldsw + _i * 8192), 16, 0, 0); } while (0)
; #define PG8_LDA(dst, b, h) do { _Pragma("unroll") for (int m = 0; m < 4; ++m) _Pragma("unroll") for (int k = 0; k < 2; ++k) dst[m][k] = *(const PG8_LAS bf16x8*)(lds + PG8_SA(b, h) + aoff + m * 2048 + k * 1024); } while (0)
; #define PG8_LDB(dst, b, h) do { _Pragma("unroll") for (int n = 0; n < 2; ++n) _Pragma("unroll") for (int k = 0; k < 2; ++k) dst[n][k] = *(const PG8_LAS bf16x8*)(lds + PG8_SB(b, h) + boff + n * 2048 + k * 1024); } while (0)
; #define PG8_MMA(ai, bj, At, Bt) do { __builtin_amdgcn_s_setprio(1); _Pragma("unroll") for (int m = 0; m < 4; ++m) _Pragma("unroll") for (int n = 0; n < 2; ++n) _Pragma("unroll") for (int k = 0; k < 2; ++k) \
;         acc[ai][bj][m][n] = __builtin_amdgcn_mfma_f32_16x16x32_bf16(Bt[n][k], At[m][k], acc[ai][bj][m][n], 0, 0, 0); __builtin_amdgcn_s_setprio(0); } while (0)
; #define PG8_WAIT_V(n) asm volatile("s_waitcnt vmcnt(" #n ")" ::: "memory")
; #define PG8_WAIT_L(n) asm volatile("s_waitcnt lgkmcnt(" #n ")" ::: "memory")
; #define PG8_BAR __builtin_amdgcn_s_barrier()
; #define PG8_SCHED __builtin_amdgcn_sched_barrier(0)
; template <class Epi, class Sched, bool ALIGN_EPI = false, bool SP2 = false>
; __device__ __forceinline__ void gemm_phase(PG8_LAS unsigned char* lds, const Gemm g, const Sched& S, const Epi& E) {
;     ...
;             PG8_LDB(B0, 0, 0); PG8_LDB(B1, 0, 1); PG8_SCHED; PG8_LDA(At, 0, 0); PG8_STAGE(PG8_SA(1, 1), a1 + hstep, voffA);
;             PG8_WAIT_V(8); PG8_WAIT_L(0); PG8_BAR; PG8_MMA(0, 0, At, B0); PG8_MMA(0, 1, At, B1); PG8_BAR; PG8_SCHED;
;             PG8_LDA(At, 0, 1); PG8_STAGE(PG8_SB(0, 0), b2, voffB); PG8_STAGE(PG8_SB(0, 1), b2 + hstep, voffB); PG8_STAGE(PG8_SA(0, 0), a2, voffA);
;     ...
;         for (int a = 0; a < 2; ++a)
; #pragma unroll
;             for (int b = 0; b < 2; ++b)
; #pragma unroll
;                 for (int m = 0; m < 4; ++m)
; #pragma unroll
;                     for (int n = 0; n < 2; ++n) acc[a][b][m][n] = (f32x4){0.f, 0.f, 0.f, 0.f};
.LBB0_96:
	s_add_u32 s18, s18, 0x80
	s_addc_u32 s19, s19, 0
	s_add_u32 s22, s22, 0x100
	s_addc_u32 s23, s23, 0
	s_mov_b32 s20, 0
	s_waitcnt vmcnt(0)
	s_mov_b64 s[56:57], 0x80
	s_add_i32 s46, s20, 2
	s_add_u32 s47, s18, 0x80
	s_addc_u32 s21, s19, 0
	s_add_i32 s54, 0, 0x10000
	s_cmp_eq_u32 s41, s20
	s_cselect_b32 s21, s1, s21
	s_cselect_b32 s20, s0, s47
	v_add_u32_e32 v64, s54, v231
	s_cselect_b32 s53, s17, s23
	s_cselect_b32 s52, s16, s22
	s_add_i32 s47, 0, 0x14000
	ds_read_b128 v[56:59], v64
	ds_read_b128 v[72:75], v64 offset:1024
	ds_read_b128 v[76:79], v64 offset:2048
	ds_read_b128 v[80:83], v64 offset:3072
	v_add_u32_e32 v64, s47, v231
	ds_read_b128 v[84:87], v64
	ds_read_b128 v[88:91], v64 offset:1024
	ds_read_b128 v[92:95], v64 offset:2048
	ds_read_b128 v[100:103], v64 offset:3072
	v_lshl_add_u64 v[66:67], s[18:19], 0, v[196:197]
	s_add_i32 m0, s33, 0xc000
	ds_read_b128 v[116:119], v233
	ds_read_b128 v[120:123], v233 offset:1024
	ds_read_b128 v[140:143], v233 offset:2048
	ds_read_b128 v[144:147], v233 offset:3072
	ds_read_b128 v[180:183], v233 offset:4096
	ds_read_b128 v[200:203], v233 offset:5120
	ds_read_b128 v[204:207], v233 offset:6144
	ds_read_b128 v[208:211], v233 offset:7168
	global_load_lds_dwordx4 v[66:67], off
	v_lshl_add_u64 v[66:67], s[18:19], 0, v[198:199]
	s_add_i32 m0, s33, 0xe000
	s_nop 0
	global_load_lds_dwordx4 v[66:67], off
	s_waitcnt vmcnt(8)
	s_waitcnt lgkmcnt(0)
	s_barrier
	v_mfma_f32_16x16x32_bf16 v[176:179], v[56:59], v[116:119], 0
	v_mfma_f32_16x16x32_bf16 v[172:175], v[76:79], v[116:119], 0
	v_mfma_f32_16x16x32_bf16 v[160:163], v[56:59], v[140:143], 0
	v_mfma_f32_16x16x32_bf16 v[156:159], v[76:79], v[140:143], 0
	v_mfma_f32_16x16x32_bf16 v[136:139], v[56:59], v[180:183], 0
	v_mfma_f32_16x16x32_bf16 v[132:135], v[76:79], v[180:183], 0
	v_mfma_f32_16x16x32_bf16 v[112:115], v[56:59], v[204:207], 0
	v_mfma_f32_16x16x32_bf16 v[108:111], v[76:79], v[204:207], 0
	v_mfma_f32_16x16x32_bf16 v[176:179], v[72:75], v[120:123], v[176:179]
	v_mfma_f32_16x16x32_bf16 v[172:175], v[80:83], v[120:123], v[172:175]
	v_mfma_f32_16x16x32_bf16 v[160:163], v[72:75], v[144:147], v[160:163]
	v_mfma_f32_16x16x32_bf16 v[156:159], v[80:83], v[144:147], v[156:159]
	v_mfma_f32_16x16x32_bf16 v[136:139], v[72:75], v[200:203], v[136:139]
	v_mfma_f32_16x16x32_bf16 v[132:135], v[80:83], v[200:203], v[132:135]
	v_mfma_f32_16x16x32_bf16 v[112:115], v[72:75], v[208:211], v[112:115]
	v_mfma_f32_16x16x32_bf16 v[108:111], v[80:83], v[208:211], v[108:111]
	v_mfma_f32_16x16x32_bf16 v[168:171], v[84:87], v[116:119], 0
	v_mfma_f32_16x16x32_bf16 v[116:119], v[92:95], v[116:119], 0
	v_mfma_f32_16x16x32_bf16 v[128:131], v[84:87], v[180:183], 0
	v_mfma_f32_16x16x32_bf16 v[124:127], v[92:95], v[180:183], 0
	v_mfma_f32_16x16x32_bf16 v[104:107], v[84:87], v[204:207], 0
	v_mfma_f32_16x16x32_bf16 v[96:99], v[92:95], v[204:207], 0
	v_mfma_f32_16x16x32_bf16 v[168:171], v[88:91], v[120:123], v[168:171]
	v_mfma_f32_16x16x32_bf16 v[116:119], v[100:103], v[120:123], v[116:119]
	v_mfma_f32_16x16x32_bf16 v[120:123], v[84:87], v[140:143], 0
	v_mfma_f32_16x16x32_bf16 v[140:143], v[92:95], v[140:143], 0
	v_mfma_f32_16x16x32_bf16 v[128:131], v[88:91], v[200:203], v[128:131]
	v_mfma_f32_16x16x32_bf16 v[124:127], v[100:103], v[200:203], v[124:127]
	v_mfma_f32_16x16x32_bf16 v[104:107], v[88:91], v[208:211], v[104:107]
	v_mfma_f32_16x16x32_bf16 v[96:99], v[100:103], v[208:211], v[96:99]
	v_mfma_f32_16x16x32_bf16 v[120:123], v[88:91], v[144:147], v[120:123]
	v_mfma_f32_16x16x32_bf16 v[140:143], v[100:103], v[144:147], v[140:143]
	s_barrier
	s_add_i32 s54, s54, s27
	v_lshl_add_u64 v[234:235], s[52:53], 0, v[190:191]
	s_mov_b32 m0, s54
	ds_read_b128 v[144:147], v233 offset:16384
	ds_read_b128 v[148:151], v233 offset:17408
	ds_read_b128 v[152:155], v233 offset:18432
	ds_read_b128 v[164:167], v233 offset:19456
	ds_read_b128 v[180:183], v233 offset:20480
	ds_read_b128 v[200:203], v233 offset:21504
	ds_read_b128 v[204:207], v233 offset:22528
	ds_read_b128 v[208:211], v233 offset:23552
	global_load_lds_dwordx4 v[234:235], off
	s_add_i32 m0, s54, 0x2000
	v_lshl_add_u64 v[236:237], s[52:53], 0, v[194:195]
	s_add_u32 s52, s52, s2
	s_addc_u32 s53, s53, 0
	s_add_i32 s47, s47, s27
	global_load_lds_dwordx4 v[236:237], off
	v_lshl_add_u64 v[238:239], s[52:53], 0, v[190:191]
	s_mov_b32 m0, s47
	v_lshl_add_u64 v[240:241], s[52:53], 0, v[194:195]
	global_load_lds_dwordx4 v[238:239], off
	s_add_i32 m0, s47, 0x2000
	v_lshl_add_u64 v[242:243], s[20:21], 0, v[188:189]
	global_load_lds_dwordx4 v[240:241], off
	s_mov_b32 m0, s33
	v_lshl_add_u64 v[244:245], s[20:21], 0, v[192:193]
	global_load_lds_dwordx4 v[242:243], off
	s_mov_b32 m0, s34
	s_nop 0
	global_load_lds_dwordx4 v[244:245], off
	s_waitcnt vmcnt(8)
	s_waitcnt lgkmcnt(0)
	s_barrier
; #define PG8_STAGE(bufoff, gbase, voff) do { _Pragma("unroll") for (int _i = 0; _i < 2; ++_i) \
;         __builtin_amdgcn_global_load_lds((const unsigned*)((const char*)(gbase) + (voff)[_i]), (PG8_LAS unsigned*)(lds + (bufoff) + ldsw + _i * 8192), 16, 0, 0); } while (0)
; #define PG8_LDA(dst, b, h) do { _Pragma("unroll") for (int m = 0; m < 4; ++m) _Pragma("unroll") for (int k = 0; k < 2; ++k) dst[m][k] = *(const PG8_LAS bf16x8*)(lds + PG8_SA(b, h) + aoff + m * 2048 + k * 1024); } while (0)
; #define PG8_LDB(dst, b, h) do { _Pragma("unroll") for (int n = 0; n < 2; ++n) _Pragma("unroll") for (int k = 0; k < 2; ++k) dst[n][k] = *(const PG8_LAS bf16x8*)(lds + PG8_SB(b, h) + boff + n * 2048 + k * 1024); } while (0)
; #define PG8_MMA(ai, bj, At, Bt) do { __builtin_amdgcn_s_setprio(1); _Pragma("unroll") for (int m = 0; m < 4; ++m) _Pragma("unroll") for (int n = 0; n < 2; ++n) _Pragma("unroll") for (int k = 0; k < 2; ++k) \
;         acc[ai][bj][m][n] = __builtin_amdgcn_mfma_f32_16x16x32_bf16(Bt[n][k], At[m][k], acc[ai][bj][m][n], 0, 0, 0); __builtin_amdgcn_s_setprio(0); } while (0)
; #define PG8_WAIT_V(n) asm volatile("s_waitcnt vmcnt(" #n ")" ::: "memory")
; #define PG8_WAIT_L(n) asm volatile("s_waitcnt lgkmcnt(" #n ")" ::: "memory")
; #define PG8_BAR __builtin_amdgcn_s_barrier()
; #define PG8_SCHED __builtin_amdgcn_sched_barrier(0)
; template <class Epi, class Sched, bool ALIGN_EPI = false, bool SP2 = false>
; __device__ __forceinline__ void gemm_phase(PG8_LAS unsigned char* lds, const Gemm g, const Sched& S, const Epi& E) {
;     ...
;             PG8_WAIT_V(8); PG8_WAIT_L(0); PG8_BAR; PG8_MMA(1, 0, At, B0); PG8_MMA(1, 1, At, B1); PG8_BAR; PG8_SCHED;
;             PG8_LDB(B0, 1, 0); PG8_LDB(B1, 1, 1); PG8_SCHED; PG8_LDA(At, 1, 0); PG8_STAGE(PG8_SA(0, 1), a2 + hstep, voffA);
;             PG8_WAIT_V(8); PG8_WAIT_L(0); PG8_BAR; PG8_MMA(0, 0, At, B0); PG8_MMA(0, 1, At, B1); PG8_BAR; PG8_SCHED;
	v_mfma_f32_16x16x32_bf16 v[66:69], v[56:59], v[144:147], 0
	v_mfma_f32_16x16x32_bf16 v[60:63], v[76:79], v[144:147], 0
	v_mfma_f32_16x16x32_bf16 v[44:47], v[56:59], v[152:155], 0
	v_mfma_f32_16x16x32_bf16 v[40:43], v[76:79], v[152:155], 0
	v_mfma_f32_16x16x32_bf16 v[28:31], v[56:59], v[180:183], 0
	v_mfma_f32_16x16x32_bf16 v[24:27], v[76:79], v[180:183], 0
	v_mfma_f32_16x16x32_bf16 v[12:15], v[56:59], v[204:207], 0
	v_mfma_f32_16x16x32_bf16 v[8:11], v[76:79], v[204:207], 0
	v_mfma_f32_16x16x32_bf16 v[66:69], v[72:75], v[148:151], v[66:69]
	v_mfma_f32_16x16x32_bf16 v[60:63], v[80:83], v[148:151], v[60:63]
	v_mfma_f32_16x16x32_bf16 v[44:47], v[72:75], v[164:167], v[44:47]
	v_mfma_f32_16x16x32_bf16 v[40:43], v[80:83], v[164:167], v[40:43]
	v_mfma_f32_16x16x32_bf16 v[28:31], v[72:75], v[200:203], v[28:31]
	v_mfma_f32_16x16x32_bf16 v[24:27], v[80:83], v[200:203], v[24:27]
	v_mfma_f32_16x16x32_bf16 v[12:15], v[72:75], v[208:211], v[12:15]
	v_mfma_f32_16x16x32_bf16 v[8:11], v[80:83], v[208:211], v[8:11]
	v_mfma_f32_16x16x32_bf16 v[52:55], v[84:87], v[144:147], 0
	v_mfma_f32_16x16x32_bf16 v[48:51], v[92:95], v[144:147], 0
	v_mfma_f32_16x16x32_bf16 v[36:39], v[84:87], v[152:155], 0
	v_mfma_f32_16x16x32_bf16 v[32:35], v[92:95], v[152:155], 0
	v_mfma_f32_16x16x32_bf16 v[20:23], v[84:87], v[180:183], 0
	v_mfma_f32_16x16x32_bf16 v[16:19], v[92:95], v[180:183], 0
	v_mfma_f32_16x16x32_bf16 v[4:7], v[84:87], v[204:207], 0
	v_mfma_f32_16x16x32_bf16 v[0:3], v[92:95], v[204:207], 0
	v_mfma_f32_16x16x32_bf16 v[52:55], v[88:91], v[148:151], v[52:55]
	v_mfma_f32_16x16x32_bf16 v[48:51], v[100:103], v[148:151], v[48:51]
	v_mfma_f32_16x16x32_bf16 v[36:39], v[88:91], v[164:167], v[36:39]
	v_mfma_f32_16x16x32_bf16 v[32:35], v[100:103], v[164:167], v[32:35]
	v_mfma_f32_16x16x32_bf16 v[20:23], v[88:91], v[200:203], v[20:23]
	v_mfma_f32_16x16x32_bf16 v[16:19], v[100:103], v[200:203], v[16:19]
	v_mfma_f32_16x16x32_bf16 v[4:7], v[88:91], v[208:211], v[4:7]
	v_mfma_f32_16x16x32_bf16 v[0:3], v[100:103], v[208:211], v[0:3]
	s_barrier
	s_add_i32 s47, 0, 0x18000
	v_add_u32_e32 v64, s47, v231
	s_add_i32 s52, 0, 0x1c000
	ds_read_b128 v[56:59], v64
	ds_read_b128 v[72:75], v64 offset:1024
	ds_read_b128 v[76:79], v64 offset:2048
	ds_read_b128 v[80:83], v64 offset:3072
	v_add_u32_e32 v64, s52, v231
	ds_read_b128 v[84:87], v64
	ds_read_b128 v[88:91], v64 offset:1024
	ds_read_b128 v[92:95], v64 offset:2048
	ds_read_b128 v[100:103], v64 offset:3072
	s_add_u32 s20, s20, s2
	s_addc_u32 s21, s21, 0
	s_mov_b32 m0, s35
	v_lshl_add_u64 v[70:71], s[20:21], 0, v[188:189]
	ds_read_b128 v[144:147], v233 offset:32768
	ds_read_b128 v[148:151], v233 offset:33792
	ds_read_b128 v[180:183], v233 offset:34816
	ds_read_b128 v[200:203], v233 offset:35840
	ds_read_b128 v[204:207], v233 offset:36864
	ds_read_b128 v[208:211], v233 offset:37888
	ds_read_b128 v[212:215], v233 offset:38912
	ds_read_b128 v[216:219], v233 offset:39936
	global_load_lds_dwordx4 v[70:71], off
	v_lshl_add_u64 v[70:71], s[20:21], 0, v[192:193]
	s_mov_b32 m0, s36
	s_nop 0
	global_load_lds_dwordx4 v[70:71], off
	s_waitcnt vmcnt(8)
	s_waitcnt lgkmcnt(0)
	s_barrier
	v_mfma_f32_16x16x32_bf16 v[152:155], v[56:59], v[144:147], v[176:179]
	v_mfma_f32_16x16x32_bf16 v[176:179], v[72:75], v[148:151], v[152:155]
	v_mfma_f32_16x16x32_bf16 v[152:155], v[76:79], v[144:147], v[172:175]
	v_mfma_f32_16x16x32_bf16 v[172:175], v[80:83], v[148:151], v[152:155]
	v_mfma_f32_16x16x32_bf16 v[152:155], v[56:59], v[180:183], v[160:163]
	v_mfma_f32_16x16x32_bf16 v[160:163], v[72:75], v[200:203], v[152:155]
	v_mfma_f32_16x16x32_bf16 v[152:155], v[76:79], v[180:183], v[156:159]
	v_mfma_f32_16x16x32_bf16 v[136:139], v[56:59], v[204:207], v[136:139]
	v_mfma_f32_16x16x32_bf16 v[132:135], v[76:79], v[204:207], v[132:135]
	v_mfma_f32_16x16x32_bf16 v[112:115], v[56:59], v[212:215], v[112:115]
	v_mfma_f32_16x16x32_bf16 v[108:111], v[76:79], v[212:215], v[108:111]
	v_mfma_f32_16x16x32_bf16 v[156:159], v[80:83], v[200:203], v[152:155]
	v_mfma_f32_16x16x32_bf16 v[136:139], v[72:75], v[208:211], v[136:139]
	v_mfma_f32_16x16x32_bf16 v[132:135], v[80:83], v[208:211], v[132:135]
	v_mfma_f32_16x16x32_bf16 v[112:115], v[72:75], v[216:219], v[112:115]
	v_mfma_f32_16x16x32_bf16 v[108:111], v[80:83], v[216:219], v[108:111]
	v_mfma_f32_16x16x32_bf16 v[116:119], v[92:95], v[144:147], v[116:119]
	v_mfma_f32_16x16x32_bf16 v[152:155], v[84:87], v[144:147], v[168:171]
	v_mfma_f32_16x16x32_bf16 v[164:167], v[100:103], v[148:151], v[116:119]
	v_mfma_f32_16x16x32_bf16 v[116:119], v[84:87], v[180:183], v[120:123]
	v_mfma_f32_16x16x32_bf16 v[168:171], v[88:91], v[148:151], v[152:155]
	v_mfma_f32_16x16x32_bf16 v[152:155], v[88:91], v[200:203], v[116:119]
	v_mfma_f32_16x16x32_bf16 v[116:119], v[92:95], v[180:183], v[140:143]
	v_mfma_f32_16x16x32_bf16 v[148:151], v[100:103], v[200:203], v[116:119]
	v_mfma_f32_16x16x32_bf16 v[116:119], v[84:87], v[204:207], v[128:131]
	v_mfma_f32_16x16x32_bf16 v[128:131], v[88:91], v[208:211], v[116:119]
	v_mfma_f32_16x16x32_bf16 v[116:119], v[92:95], v[204:207], v[124:127]
	v_mfma_f32_16x16x32_bf16 v[104:107], v[84:87], v[212:215], v[104:107]
	v_mfma_f32_16x16x32_bf16 v[96:99], v[92:95], v[212:215], v[96:99]
	v_mfma_f32_16x16x32_bf16 v[124:127], v[100:103], v[208:211], v[116:119]
	v_mfma_f32_16x16x32_bf16 v[104:107], v[88:91], v[216:219], v[104:107]
	v_mfma_f32_16x16x32_bf16 v[96:99], v[100:103], v[216:219], v[96:99]
	s_barrier
; #define PG8_STAGE(bufoff, gbase, voff) do { _Pragma("unroll") for (int _i = 0; _i < 2; ++_i) \
;         __builtin_amdgcn_global_load_lds((const unsigned*)((const char*)(gbase) + (voff)[_i]), (PG8_LAS unsigned*)(lds + (bufoff) + ldsw + _i * 8192), 16, 0, 0); } while (0)
; #define PG8_LDA(dst, b, h) do { _Pragma("unroll") for (int m = 0; m < 4; ++m) _Pragma("unroll") for (int k = 0; k < 2; ++k) dst[m][k] = *(const PG8_LAS bf16x8*)(lds + PG8_SA(b, h) + aoff + m * 2048 + k * 1024); } while (0)
; #define PG8_MMA(ai, bj, At, Bt) do { __builtin_amdgcn_s_setprio(1); _Pragma("unroll") for (int m = 0; m < 4; ++m) _Pragma("unroll") for (int n = 0; n < 2; ++n) _Pragma("unroll") for (int k = 0; k < 2; ++k) \
;         acc[ai][bj][m][n] = __builtin_amdgcn_mfma_f32_16x16x32_bf16(Bt[n][k], At[m][k], acc[ai][bj][m][n], 0, 0, 0); __builtin_amdgcn_s_setprio(0); } while (0)
; #define PG8_WAIT_V(n) asm volatile("s_waitcnt vmcnt(" #n ")" ::: "memory")
; #define PG8_WAIT_L(n) asm volatile("s_waitcnt lgkmcnt(" #n ")" ::: "memory")
; #define PG8_BAR __builtin_amdgcn_s_barrier()
; #define PG8_SCHED __builtin_amdgcn_sched_barrier(0)
; template <class Epi, class Sched, bool ALIGN_EPI = false, bool SP2 = false>
; __device__ __forceinline__ void gemm_phase(PG8_LAS unsigned char* lds, const Gemm g, const Sched& S, const Epi& E) {
;     ...
;             PG8_LDA(At, 1, 1); PG8_STAGE(PG8_SB(1, 0), b3, voffB); PG8_STAGE(PG8_SB(1, 1), b3 + hstep, voffB); PG8_STAGE(PG8_SA(1, 0), a3, voffA);
;             PG8_WAIT_V(8); PG8_WAIT_L(0); PG8_BAR; PG8_MMA(1, 0, At, B0); PG8_MMA(1, 1, At, B1); PG8_BAR; PG8_SCHED;
	s_add_i32 s20, s47, s27
	v_lshl_add_u64 v[70:71], v[234:235], 0, s[56:57]
	s_mov_b32 m0, s20
	ds_read_b128 v[116:119], v233 offset:49152
	ds_read_b128 v[120:123], v233 offset:50176
	ds_read_b128 v[140:143], v233 offset:51200
	ds_read_b128 v[144:147], v233 offset:52224
	ds_read_b128 v[180:183], v233 offset:53248
	ds_read_b128 v[200:203], v233 offset:54272
	ds_read_b128 v[204:207], v233 offset:55296
	ds_read_b128 v[208:211], v233 offset:56320
	global_load_lds_dwordx4 v[70:71], off
	v_lshl_add_u64 v[70:71], v[236:237], 0, s[56:57]
	s_add_i32 m0, s20, 0x2000
	s_add_i32 s20, s52, s27
	global_load_lds_dwordx4 v[70:71], off
	v_lshl_add_u64 v[70:71], v[238:239], 0, s[56:57]
	s_mov_b32 m0, s20
	s_nop 0
	global_load_lds_dwordx4 v[70:71], off
	v_lshl_add_u64 v[70:71], v[240:241], 0, s[56:57]
	s_add_i32 m0, s20, 0x2000
	s_nop 0
	global_load_lds_dwordx4 v[70:71], off
	v_lshl_add_u64 v[70:71], v[242:243], 0, s[56:57]
	s_mov_b32 m0, s39
	s_nop 0
	global_load_lds_dwordx4 v[70:71], off
	v_lshl_add_u64 v[70:71], v[244:245], 0, s[56:57]
	s_mov_b32 m0, s40
	s_nop 0
	global_load_lds_dwordx4 v[70:71], off
	s_waitcnt vmcnt(8)
	s_waitcnt lgkmcnt(0)
	s_barrier
	v_mfma_f32_16x16x32_bf16 v[66:69], v[56:59], v[116:119], v[66:69]
	v_mfma_f32_16x16x32_bf16 v[60:63], v[76:79], v[116:119], v[60:63]
	v_mfma_f32_16x16x32_bf16 v[44:47], v[56:59], v[140:143], v[44:47]
	v_mfma_f32_16x16x32_bf16 v[40:43], v[76:79], v[140:143], v[40:43]
	v_mfma_f32_16x16x32_bf16 v[28:31], v[56:59], v[180:183], v[28:31]
	v_mfma_f32_16x16x32_bf16 v[24:27], v[76:79], v[180:183], v[24:27]
	v_mfma_f32_16x16x32_bf16 v[12:15], v[56:59], v[204:207], v[12:15]
	v_mfma_f32_16x16x32_bf16 v[8:11], v[76:79], v[204:207], v[8:11]
	v_mfma_f32_16x16x32_bf16 v[68:71], v[72:75], v[120:123], v[66:69]
	v_mfma_f32_16x16x32_bf16 v[60:63], v[80:83], v[120:123], v[60:63]
	v_mfma_f32_16x16x32_bf16 v[44:47], v[72:75], v[144:147], v[44:47]
	v_mfma_f32_16x16x32_bf16 v[40:43], v[80:83], v[144:147], v[40:43]
	v_mfma_f32_16x16x32_bf16 v[28:31], v[72:75], v[200:203], v[28:31]
	v_mfma_f32_16x16x32_bf16 v[24:27], v[80:83], v[200:203], v[24:27]
	v_mfma_f32_16x16x32_bf16 v[12:15], v[72:75], v[208:211], v[12:15]
	v_mfma_f32_16x16x32_bf16 v[8:11], v[80:83], v[208:211], v[8:11]
	v_mfma_f32_16x16x32_bf16 v[52:55], v[84:87], v[116:119], v[52:55]
	v_mfma_f32_16x16x32_bf16 v[48:51], v[92:95], v[116:119], v[48:51]
	v_mfma_f32_16x16x32_bf16 v[36:39], v[84:87], v[140:143], v[36:39]
	v_mfma_f32_16x16x32_bf16 v[32:35], v[92:95], v[140:143], v[32:35]
	v_mfma_f32_16x16x32_bf16 v[20:23], v[84:87], v[180:183], v[20:23]
	v_mfma_f32_16x16x32_bf16 v[16:19], v[92:95], v[180:183], v[16:19]
	v_mfma_f32_16x16x32_bf16 v[4:7], v[84:87], v[204:207], v[4:7]
	v_mfma_f32_16x16x32_bf16 v[0:3], v[92:95], v[204:207], v[0:3]
	v_mfma_f32_16x16x32_bf16 v[52:55], v[88:91], v[120:123], v[52:55]
	v_mfma_f32_16x16x32_bf16 v[48:51], v[100:103], v[120:123], v[48:51]
	v_mfma_f32_16x16x32_bf16 v[36:39], v[88:91], v[144:147], v[36:39]
	v_mfma_f32_16x16x32_bf16 v[32:35], v[100:103], v[144:147], v[32:35]
	v_mfma_f32_16x16x32_bf16 v[20:23], v[88:91], v[200:203], v[20:23]
	v_mfma_f32_16x16x32_bf16 v[16:19], v[100:103], v[200:203], v[16:19]
	v_mfma_f32_16x16x32_bf16 v[4:7], v[88:91], v[208:211], v[4:7]
	v_mfma_f32_16x16x32_bf16 v[0:3], v[100:103], v[208:211], v[0:3]
	s_barrier
	s_add_u32 s18, s18, 0x100
	s_addc_u32 s19, s19, 0
	s_add_u32 s22, s22, 0x100
	s_addc_u32 s23, s23, 0
	s_cmp_ge_u32 s46, s38
	s_mov_b32 s20, s46

; #define PG8_STAGE(bufoff, gbase, voff) do { _Pragma("unroll") for (int _i = 0; _i < 2; ++_i) \
;         __builtin_amdgcn_global_load_lds((const unsigned*)((const char*)(gbase) + (voff)[_i]), (PG8_LAS unsigned*)(lds + (bufoff) + ldsw + _i * 8192), 16, 0, 0); } while (0)
; #define PG8_LDA(dst, b, h) do { _Pragma("unroll") for (int m = 0; m < 4; ++m) _Pragma("unroll") for (int k = 0; k < 2; ++k) dst[m][k] = *(const PG8_LAS bf16x8*)(lds + PG8_SA(b, h) + aoff + m * 2048 + k * 1024); } while (0)
; #define PG8_LDB(dst, b, h) do { _Pragma("unroll") for (int n = 0; n < 2; ++n) _Pragma("unroll") for (int k = 0; k < 2; ++k) dst[n][k] = *(const PG8_LAS bf16x8*)(lds + PG8_SB(b, h) + boff + n * 2048 + k * 1024); } while (0)
; #define PG8_MMA(ai, bj, At, Bt) do { __builtin_amdgcn_s_setprio(1); _Pragma("unroll") for (int m = 0; m < 4; ++m) _Pragma("unroll") for (int n = 0; n < 2; ++n) _Pragma("unroll") for (int k = 0; k < 2; ++k) \
;         acc[ai][bj][m][n] = __builtin_amdgcn_mfma_f32_16x16x32_bf16(Bt[n][k], At[m][k], acc[ai][bj][m][n], 0, 0, 0); __builtin_amdgcn_s_setprio(0); } while (0)
; #define PG8_WAIT_V(n) asm volatile("s_waitcnt vmcnt(" #n ")" ::: "memory")
; #define PG8_WAIT_L(n) asm volatile("s_waitcnt lgkmcnt(" #n ")" ::: "memory")
; #define PG8_BAR __builtin_amdgcn_s_barrier()
; #define PG8_SCHED __builtin_amdgcn_sched_barrier(0)
; template <class Epi, class Sched, bool ALIGN_EPI = false, bool SP2 = false>
; __device__ __forceinline__ void gemm_phase(PG8_LAS unsigned char* lds, const Gemm g, const Sched& S, const Epi& E) {
;     ...
;             PG8_LDB(B0, 0, 0); PG8_LDB(B1, 0, 1); PG8_SCHED; PG8_LDA(At, 0, 0); PG8_STAGE(PG8_SA(1, 1), a1 + hstep, voffA);
;             PG8_WAIT_V(8); PG8_WAIT_L(0); PG8_BAR; PG8_MMA(0, 0, At, B0); PG8_MMA(0, 1, At, B1); PG8_BAR; PG8_SCHED;
;             PG8_LDA(At, 0, 1); PG8_STAGE(PG8_SB(0, 0), b2, voffB); PG8_STAGE(PG8_SB(0, 1), b2 + hstep, voffB); PG8_STAGE(PG8_SA(0, 0), a2, voffA);
;     ...
;         for (int a = 0; a < 2; ++a)
; #pragma unroll
;             for (int b = 0; b < 2; ++b)
; #pragma unroll
;                 for (int m = 0; m < 4; ++m)
; #pragma unroll
;                     for (int n = 0; n < 2; ++n) acc[a][b][m][n] = (f32x4){0.f, 0.f, 0.f, 0.f};
.LBB0_251:
	s_ashr_i32 s9, s8, 31
	s_lshl_b64 s[10:11], s[8:9], 19
	s_add_u32 s10, s66, s10
	s_addc_u32 s11, s67, s11
	s_and_b64 s[12:13], s[42:43], exec
	s_cselect_b32 s9, s11, s17
	s_cselect_b32 s40, s10, s16
	s_ashr_i32 s7, s6, 31
	s_lshl_b64 s[12:13], s[6:7], 19
	s_add_u32 s12, s25, s12
	s_addc_u32 s13, s26, s13
	s_and_b64 s[20:21], s[42:43], exec
	s_cselect_b32 s7, s13, s19
	s_cselect_b32 s41, s12, s18
	s_add_u32 s16, s16, 0x40080
	s_addc_u32 s17, s17, 0
	s_add_u32 s44, s18, 0x100
	s_addc_u32 s45, s19, 0
	s_mov_b32 s46, -2
	s_mov_b64 s[52:53], 0x80
	s_add_u32 s18, s16, 0xfffc0080
	s_addc_u32 s19, s17, -1
	s_add_i32 s47, 0, 0x10000
	s_cmp_eq_u32 s46, 12
	s_cselect_b32 s21, s9, s19
	s_cselect_b32 s20, s40, s18
	v_add_u32_e32 v64, s47, v152
	s_cselect_b32 s19, s7, s45
	s_cselect_b32 s18, s41, s44
	s_add_i32 s50, 0, 0x14000
	ds_read_b128 v[142:145], v64
	ds_read_b128 v[158:161], v64 offset:1024
	ds_read_b128 v[162:165], v64 offset:2048
	ds_read_b128 v[166:169], v64 offset:3072
	v_add_u32_e32 v64, s50, v152
	ds_read_b128 v[170:173], v64
	ds_read_b128 v[174:177], v64 offset:1024
	ds_read_b128 v[178:181], v64 offset:2048
	ds_read_b128 v[188:191], v64 offset:3072
	v_lshl_add_u64 v[146:147], s[16:17], 0, v[138:139]
	s_add_i32 m0, s28, 0xc000
	ds_read_b128 v[192:195], v156
	ds_read_b128 v[196:199], v156 offset:1024
	ds_read_b128 v[200:203], v156 offset:2048
	ds_read_b128 v[204:207], v156 offset:3072
	ds_read_b128 v[208:211], v156 offset:4096
	ds_read_b128 v[212:215], v156 offset:5120
	ds_read_b128 v[216:219], v156 offset:6144
	ds_read_b128 v[230:233], v156 offset:7168
	global_load_lds_dwordx4 v[146:147], off
	v_lshl_add_u64 v[146:147], s[16:17], 0, v[140:141]
	s_add_i32 m0, s28, 0xe000
	s_nop 0
	global_load_lds_dwordx4 v[146:147], off
	s_waitcnt vmcnt(8)
	s_waitcnt lgkmcnt(0)
	s_barrier
	v_mfma_f32_16x16x32_bf16 v[126:129], v[142:145], v[192:195], 0
	v_mfma_f32_16x16x32_bf16 v[122:125], v[162:165], v[192:195], 0
	v_mfma_f32_16x16x32_bf16 v[114:117], v[142:145], v[200:203], 0
	v_mfma_f32_16x16x32_bf16 v[106:109], v[162:165], v[200:203], 0
	v_mfma_f32_16x16x32_bf16 v[102:105], v[142:145], v[208:211], 0
	v_mfma_f32_16x16x32_bf16 v[94:97], v[162:165], v[208:211], 0
	v_mfma_f32_16x16x32_bf16 v[82:85], v[142:145], v[216:219], 0
	v_mfma_f32_16x16x32_bf16 v[74:77], v[162:165], v[216:219], 0
	v_mfma_f32_16x16x32_bf16 v[126:129], v[158:161], v[196:199], v[126:129]
	v_mfma_f32_16x16x32_bf16 v[122:125], v[166:169], v[196:199], v[122:125]
	v_mfma_f32_16x16x32_bf16 v[114:117], v[158:161], v[204:207], v[114:117]
	v_mfma_f32_16x16x32_bf16 v[106:109], v[166:169], v[204:207], v[106:109]
	v_mfma_f32_16x16x32_bf16 v[102:105], v[158:161], v[212:215], v[102:105]
	v_mfma_f32_16x16x32_bf16 v[94:97], v[166:169], v[212:215], v[94:97]
	v_mfma_f32_16x16x32_bf16 v[82:85], v[158:161], v[230:233], v[82:85]
	v_mfma_f32_16x16x32_bf16 v[74:77], v[166:169], v[230:233], v[74:77]
	v_mfma_f32_16x16x32_bf16 v[118:121], v[170:173], v[192:195], 0
	v_mfma_f32_16x16x32_bf16 v[110:113], v[178:181], v[192:195], 0
	v_mfma_f32_16x16x32_bf16 v[98:101], v[170:173], v[200:203], 0
	v_mfma_f32_16x16x32_bf16 v[90:93], v[178:181], v[200:203], 0
	v_mfma_f32_16x16x32_bf16 v[86:89], v[170:173], v[208:211], 0
	v_mfma_f32_16x16x32_bf16 v[78:81], v[178:181], v[208:211], 0
	v_mfma_f32_16x16x32_bf16 v[70:73], v[170:173], v[216:219], 0
	v_mfma_f32_16x16x32_bf16 v[66:69], v[178:181], v[216:219], 0
	v_mfma_f32_16x16x32_bf16 v[118:121], v[174:177], v[196:199], v[118:121]
	v_mfma_f32_16x16x32_bf16 v[110:113], v[188:191], v[196:199], v[110:113]
	v_mfma_f32_16x16x32_bf16 v[98:101], v[174:177], v[204:207], v[98:101]
	v_mfma_f32_16x16x32_bf16 v[90:93], v[188:191], v[204:207], v[90:93]
	v_mfma_f32_16x16x32_bf16 v[86:89], v[174:177], v[212:215], v[86:89]
	v_mfma_f32_16x16x32_bf16 v[78:81], v[188:191], v[212:215], v[78:81]
	v_mfma_f32_16x16x32_bf16 v[70:73], v[174:177], v[230:233], v[70:73]
	v_mfma_f32_16x16x32_bf16 v[66:69], v[188:191], v[230:233], v[66:69]
	s_barrier
	s_add_i32 s47, s47, s27
	v_lshl_add_u64 v[146:147], s[18:19], 0, v[134:135]
	s_mov_b32 m0, s47
	ds_read_b128 v[192:195], v156 offset:16384
	ds_read_b128 v[196:199], v156 offset:17408
	ds_read_b128 v[200:203], v156 offset:18432
	ds_read_b128 v[204:207], v156 offset:19456
	ds_read_b128 v[208:211], v156 offset:20480
	ds_read_b128 v[212:215], v156 offset:21504
	ds_read_b128 v[216:219], v156 offset:22528
	ds_read_b128 v[230:233], v156 offset:23552
	global_load_lds_dwordx4 v[146:147], off
	s_add_i32 m0, s47, 0x2000
	s_add_u32 s48, s18, 0x40000
	v_lshl_add_u64 v[150:151], s[18:19], 0, v[130:131]
	s_addc_u32 s49, s19, 0
	s_add_i32 s47, s50, s27
	global_load_lds_dwordx4 v[150:151], off
	v_lshl_add_u64 v[182:183], s[48:49], 0, v[134:135]
	s_mov_b32 m0, s47
	v_lshl_add_u64 v[234:235], s[20:21], 0, v[132:133]
	global_load_lds_dwordx4 v[182:183], off
	v_lshl_add_u64 v[182:183], s[48:49], 0, v[130:131]
	s_add_i32 m0, s47, 0x2000
	s_nop 0
	global_load_lds_dwordx4 v[182:183], off
	v_lshl_add_u64 v[182:183], s[20:21], 0, v[136:137]
	s_mov_b32 m0, s28
	s_nop 0
	global_load_lds_dwordx4 v[182:183], off
	s_mov_b32 m0, s29
	s_nop 0
	global_load_lds_dwordx4 v[234:235], off
	s_waitcnt vmcnt(8)
	s_waitcnt lgkmcnt(0)
	s_barrier
; #define PG8_STAGE(bufoff, gbase, voff) do { _Pragma("unroll") for (int _i = 0; _i < 2; ++_i) \
;         __builtin_amdgcn_global_load_lds((const unsigned*)((const char*)(gbase) + (voff)[_i]), (PG8_LAS unsigned*)(lds + (bufoff) + ldsw + _i * 8192), 16, 0, 0); } while (0)
; #define PG8_LDA(dst, b, h) do { _Pragma("unroll") for (int m = 0; m < 4; ++m) _Pragma("unroll") for (int k = 0; k < 2; ++k) dst[m][k] = *(const PG8_LAS bf16x8*)(lds + PG8_SA(b, h) + aoff + m * 2048 + k * 1024); } while (0)
; #define PG8_LDB(dst, b, h) do { _Pragma("unroll") for (int n = 0; n < 2; ++n) _Pragma("unroll") for (int k = 0; k < 2; ++k) dst[n][k] = *(const PG8_LAS bf16x8*)(lds + PG8_SB(b, h) + boff + n * 2048 + k * 1024); } while (0)
; #define PG8_MMA(ai, bj, At, Bt) do { __builtin_amdgcn_s_setprio(1); _Pragma("unroll") for (int m = 0; m < 4; ++m) _Pragma("unroll") for (int n = 0; n < 2; ++n) _Pragma("unroll") for (int k = 0; k < 2; ++k) \
;         acc[ai][bj][m][n] = __builtin_amdgcn_mfma_f32_16x16x32_bf16(Bt[n][k], At[m][k], acc[ai][bj][m][n], 0, 0, 0); __builtin_amdgcn_s_setprio(0); } while (0)
; #define PG8_WAIT_V(n) asm volatile("s_waitcnt vmcnt(" #n ")" ::: "memory")
; #define PG8_WAIT_L(n) asm volatile("s_waitcnt lgkmcnt(" #n ")" ::: "memory")
; #define PG8_BAR __builtin_amdgcn_s_barrier()
; #define PG8_SCHED __builtin_amdgcn_sched_barrier(0)
; template <class Epi, class Sched, bool ALIGN_EPI = false, bool SP2 = false>
; __device__ __forceinline__ void gemm_phase(PG8_LAS unsigned char* lds, const Gemm g, const Sched& S, const Epi& E) {
;     ...
;             PG8_WAIT_V(8); PG8_WAIT_L(0); PG8_BAR; PG8_MMA(1, 0, At, B0); PG8_MMA(1, 1, At, B1); PG8_BAR; PG8_SCHED;
;             PG8_LDB(B0, 1, 0); PG8_LDB(B1, 1, 1); PG8_SCHED; PG8_LDA(At, 1, 0); PG8_STAGE(PG8_SA(0, 1), a2 + hstep, voffA);
;             PG8_WAIT_V(8); PG8_WAIT_L(0); PG8_BAR; PG8_MMA(0, 0, At, B0); PG8_MMA(0, 1, At, B1); PG8_BAR; PG8_SCHED;
	v_mfma_f32_16x16x32_bf16 v[60:63], v[142:145], v[192:195], 0
	v_mfma_f32_16x16x32_bf16 v[56:59], v[162:165], v[192:195], 0
	v_mfma_f32_16x16x32_bf16 v[48:51], v[142:145], v[200:203], 0
	v_mfma_f32_16x16x32_bf16 v[40:43], v[162:165], v[200:203], 0
	v_mfma_f32_16x16x32_bf16 v[36:39], v[142:145], v[208:211], 0
	v_mfma_f32_16x16x32_bf16 v[28:31], v[162:165], v[208:211], 0
	v_mfma_f32_16x16x32_bf16 v[20:23], v[142:145], v[216:219], 0
	v_mfma_f32_16x16x32_bf16 v[12:15], v[162:165], v[216:219], 0
	v_mfma_f32_16x16x32_bf16 v[60:63], v[158:161], v[196:199], v[60:63]
	v_mfma_f32_16x16x32_bf16 v[56:59], v[166:169], v[196:199], v[56:59]
	v_mfma_f32_16x16x32_bf16 v[48:51], v[158:161], v[204:207], v[48:51]
	v_mfma_f32_16x16x32_bf16 v[40:43], v[166:169], v[204:207], v[40:43]
	v_mfma_f32_16x16x32_bf16 v[36:39], v[158:161], v[212:215], v[36:39]
	v_mfma_f32_16x16x32_bf16 v[28:31], v[166:169], v[212:215], v[28:31]
	v_mfma_f32_16x16x32_bf16 v[20:23], v[158:161], v[230:233], v[20:23]
	v_mfma_f32_16x16x32_bf16 v[12:15], v[166:169], v[230:233], v[12:15]
	v_mfma_f32_16x16x32_bf16 v[52:55], v[170:173], v[192:195], 0
	v_mfma_f32_16x16x32_bf16 v[44:47], v[178:181], v[192:195], 0
	v_mfma_f32_16x16x32_bf16 v[32:35], v[170:173], v[200:203], 0
	v_mfma_f32_16x16x32_bf16 v[24:27], v[178:181], v[200:203], 0
	v_mfma_f32_16x16x32_bf16 v[16:19], v[170:173], v[208:211], 0
	v_mfma_f32_16x16x32_bf16 v[8:11], v[178:181], v[208:211], 0
	v_mfma_f32_16x16x32_bf16 v[4:7], v[170:173], v[216:219], 0
	v_mfma_f32_16x16x32_bf16 v[0:3], v[178:181], v[216:219], 0
	v_mfma_f32_16x16x32_bf16 v[52:55], v[174:177], v[196:199], v[52:55]
	v_mfma_f32_16x16x32_bf16 v[44:47], v[188:191], v[196:199], v[44:47]
	v_mfma_f32_16x16x32_bf16 v[32:35], v[174:177], v[204:207], v[32:35]
	v_mfma_f32_16x16x32_bf16 v[24:27], v[188:191], v[204:207], v[24:27]
	v_mfma_f32_16x16x32_bf16 v[16:19], v[174:177], v[212:215], v[16:19]
	v_mfma_f32_16x16x32_bf16 v[8:11], v[188:191], v[212:215], v[8:11]
	v_mfma_f32_16x16x32_bf16 v[4:7], v[174:177], v[230:233], v[4:7]
	v_mfma_f32_16x16x32_bf16 v[0:3], v[188:191], v[230:233], v[0:3]
	s_barrier
	s_add_i32 s47, 0, 0x18000
	v_add_u32_e32 v64, s47, v152
	s_add_i32 s48, 0, 0x1c000
	ds_read_b128 v[142:145], v64
	ds_read_b128 v[158:161], v64 offset:1024
	ds_read_b128 v[162:165], v64 offset:2048
	ds_read_b128 v[166:169], v64 offset:3072
	v_add_u32_e32 v64, s48, v152
	ds_read_b128 v[170:173], v64
	ds_read_b128 v[174:177], v64 offset:1024
	ds_read_b128 v[178:181], v64 offset:2048
	ds_read_b128 v[188:191], v64 offset:3072
	s_add_u32 s20, s20, 0x40000
	s_addc_u32 s21, s21, 0
	s_mov_b32 m0, s33
	v_lshl_add_u64 v[236:237], s[20:21], 0, v[136:137]
	ds_read_b128 v[192:195], v156 offset:32768
	ds_read_b128 v[196:199], v156 offset:33792
	ds_read_b128 v[200:203], v156 offset:34816
	ds_read_b128 v[204:207], v156 offset:35840
	ds_read_b128 v[208:211], v156 offset:36864
	ds_read_b128 v[212:215], v156 offset:37888
	ds_read_b128 v[216:219], v156 offset:38912
	ds_read_b128 v[230:233], v156 offset:39936
	global_load_lds_dwordx4 v[236:237], off
	v_lshl_add_u64 v[236:237], s[20:21], 0, v[132:133]
	s_mov_b32 m0, s34
	s_nop 0
	global_load_lds_dwordx4 v[236:237], off
	s_waitcnt vmcnt(8)
	s_waitcnt lgkmcnt(0)
	s_barrier
	v_mfma_f32_16x16x32_bf16 v[126:129], v[142:145], v[192:195], v[126:129]
	v_mfma_f32_16x16x32_bf16 v[122:125], v[162:165], v[192:195], v[122:125]
	v_mfma_f32_16x16x32_bf16 v[114:117], v[142:145], v[200:203], v[114:117]
	v_mfma_f32_16x16x32_bf16 v[106:109], v[162:165], v[200:203], v[106:109]
	v_mfma_f32_16x16x32_bf16 v[102:105], v[142:145], v[208:211], v[102:105]
	v_mfma_f32_16x16x32_bf16 v[94:97], v[162:165], v[208:211], v[94:97]
	v_mfma_f32_16x16x32_bf16 v[82:85], v[142:145], v[216:219], v[82:85]
	v_mfma_f32_16x16x32_bf16 v[74:77], v[162:165], v[216:219], v[74:77]
	v_mfma_f32_16x16x32_bf16 v[126:129], v[158:161], v[196:199], v[126:129]
	v_mfma_f32_16x16x32_bf16 v[122:125], v[166:169], v[196:199], v[122:125]
	v_mfma_f32_16x16x32_bf16 v[114:117], v[158:161], v[204:207], v[114:117]
	v_mfma_f32_16x16x32_bf16 v[106:109], v[166:169], v[204:207], v[106:109]
	v_mfma_f32_16x16x32_bf16 v[102:105], v[158:161], v[212:215], v[102:105]
	v_mfma_f32_16x16x32_bf16 v[94:97], v[166:169], v[212:215], v[94:97]
	v_mfma_f32_16x16x32_bf16 v[82:85], v[158:161], v[230:233], v[82:85]
	v_mfma_f32_16x16x32_bf16 v[74:77], v[166:169], v[230:233], v[74:77]
	v_mfma_f32_16x16x32_bf16 v[118:121], v[170:173], v[192:195], v[118:121]
	v_mfma_f32_16x16x32_bf16 v[110:113], v[178:181], v[192:195], v[110:113]
	v_mfma_f32_16x16x32_bf16 v[98:101], v[170:173], v[200:203], v[98:101]
	v_mfma_f32_16x16x32_bf16 v[90:93], v[178:181], v[200:203], v[90:93]
	v_mfma_f32_16x16x32_bf16 v[86:89], v[170:173], v[208:211], v[86:89]
	v_mfma_f32_16x16x32_bf16 v[78:81], v[178:181], v[208:211], v[78:81]
	v_mfma_f32_16x16x32_bf16 v[70:73], v[170:173], v[216:219], v[70:73]
	v_mfma_f32_16x16x32_bf16 v[66:69], v[178:181], v[216:219], v[66:69]
	v_mfma_f32_16x16x32_bf16 v[118:121], v[174:177], v[196:199], v[118:121]
	v_mfma_f32_16x16x32_bf16 v[110:113], v[188:191], v[196:199], v[110:113]
	v_mfma_f32_16x16x32_bf16 v[98:101], v[174:177], v[204:207], v[98:101]
	v_mfma_f32_16x16x32_bf16 v[90:93], v[188:191], v[204:207], v[90:93]
	v_mfma_f32_16x16x32_bf16 v[86:89], v[174:177], v[212:215], v[86:89]
	v_mfma_f32_16x16x32_bf16 v[78:81], v[188:191], v[212:215], v[78:81]
	v_mfma_f32_16x16x32_bf16 v[70:73], v[174:177], v[230:233], v[70:73]
	v_mfma_f32_16x16x32_bf16 v[66:69], v[188:191], v[230:233], v[66:69]
	s_barrier
; #define PG8_STAGE(bufoff, gbase, voff) do { _Pragma("unroll") for (int _i = 0; _i < 2; ++_i) \
;         __builtin_amdgcn_global_load_lds((const unsigned*)((const char*)(gbase) + (voff)[_i]), (PG8_LAS unsigned*)(lds + (bufoff) + ldsw + _i * 8192), 16, 0, 0); } while (0)
; #define PG8_LDA(dst, b, h) do { _Pragma("unroll") for (int m = 0; m < 4; ++m) _Pragma("unroll") for (int k = 0; k < 2; ++k) dst[m][k] = *(const PG8_LAS bf16x8*)(lds + PG8_SA(b, h) + aoff + m * 2048 + k * 1024); } while (0)
; #define PG8_MMA(ai, bj, At, Bt) do { __builtin_amdgcn_s_setprio(1); _Pragma("unroll") for (int m = 0; m < 4; ++m) _Pragma("unroll") for (int n = 0; n < 2; ++n) _Pragma("unroll") for (int k = 0; k < 2; ++k) \
;         acc[ai][bj][m][n] = __builtin_amdgcn_mfma_f32_16x16x32_bf16(Bt[n][k], At[m][k], acc[ai][bj][m][n], 0, 0, 0); __builtin_amdgcn_s_setprio(0); } while (0)
; #define PG8_WAIT_V(n) asm volatile("s_waitcnt vmcnt(" #n ")" ::: "memory")
; #define PG8_WAIT_L(n) asm volatile("s_waitcnt lgkmcnt(" #n ")" ::: "memory")
; #define PG8_BAR __builtin_amdgcn_s_barrier()
; #define PG8_SCHED __builtin_amdgcn_sched_barrier(0)
; template <class Epi, class Sched, bool ALIGN_EPI = false, bool SP2 = false>
; __device__ __forceinline__ void gemm_phase(PG8_LAS unsigned char* lds, const Gemm g, const Sched& S, const Epi& E) {
;     ...
;             PG8_LDA(At, 1, 1); PG8_STAGE(PG8_SB(1, 0), b3, voffB); PG8_STAGE(PG8_SB(1, 1), b3 + hstep, voffB); PG8_STAGE(PG8_SA(1, 0), a3, voffA);
;             PG8_WAIT_V(8); PG8_WAIT_L(0); PG8_BAR; PG8_MMA(1, 0, At, B0); PG8_MMA(1, 1, At, B1); PG8_BAR; PG8_SCHED;
	s_add_i32 s20, s47, s27
	v_lshl_add_u64 v[146:147], v[146:147], 0, s[52:53]
	s_mov_b32 m0, s20
	ds_read_b128 v[192:195], v156 offset:49152
	ds_read_b128 v[196:199], v156 offset:50176
	ds_read_b128 v[200:203], v156 offset:51200
	ds_read_b128 v[204:207], v156 offset:52224
	ds_read_b128 v[208:211], v156 offset:53248
	ds_read_b128 v[212:215], v156 offset:54272
	ds_read_b128 v[216:219], v156 offset:55296
	ds_read_b128 v[230:233], v156 offset:56320
	global_load_lds_dwordx4 v[146:147], off
	s_add_i32 m0, s20, 0x2000
	s_add_u32 s18, s18, 0x40080
	v_lshl_add_u64 v[146:147], v[150:151], 0, s[52:53]
	s_addc_u32 s19, s19, 0
	s_add_i32 s20, s48, s27
	global_load_lds_dwordx4 v[146:147], off
	v_lshl_add_u64 v[146:147], s[18:19], 0, v[134:135]
	s_mov_b32 m0, s20
	s_nop 0
	global_load_lds_dwordx4 v[146:147], off
	v_lshl_add_u64 v[146:147], s[18:19], 0, v[130:131]
	s_add_i32 m0, s20, 0x2000
	s_nop 0
	global_load_lds_dwordx4 v[146:147], off
	v_lshl_add_u64 v[146:147], v[182:183], 0, s[52:53]
	s_mov_b32 m0, s35
	s_nop 0
	global_load_lds_dwordx4 v[146:147], off
	v_lshl_add_u64 v[146:147], v[234:235], 0, s[52:53]
	s_mov_b32 m0, s36
	s_nop 0
	global_load_lds_dwordx4 v[146:147], off
	s_waitcnt vmcnt(8)
	s_waitcnt lgkmcnt(0)
	s_barrier
	v_mfma_f32_16x16x32_bf16 v[60:63], v[142:145], v[192:195], v[60:63]
	v_mfma_f32_16x16x32_bf16 v[56:59], v[162:165], v[192:195], v[56:59]
	v_mfma_f32_16x16x32_bf16 v[48:51], v[142:145], v[200:203], v[48:51]
	v_mfma_f32_16x16x32_bf16 v[40:43], v[162:165], v[200:203], v[40:43]
	v_mfma_f32_16x16x32_bf16 v[36:39], v[142:145], v[208:211], v[36:39]
	v_mfma_f32_16x16x32_bf16 v[28:31], v[162:165], v[208:211], v[28:31]
	v_mfma_f32_16x16x32_bf16 v[20:23], v[142:145], v[216:219], v[20:23]
	v_mfma_f32_16x16x32_bf16 v[12:15], v[162:165], v[216:219], v[12:15]
	v_mfma_f32_16x16x32_bf16 v[60:63], v[158:161], v[196:199], v[60:63]
	v_mfma_f32_16x16x32_bf16 v[56:59], v[166:169], v[196:199], v[56:59]
	v_mfma_f32_16x16x32_bf16 v[48:51], v[158:161], v[204:207], v[48:51]
	v_mfma_f32_16x16x32_bf16 v[40:43], v[166:169], v[204:207], v[40:43]
	v_mfma_f32_16x16x32_bf16 v[36:39], v[158:161], v[212:215], v[36:39]
	v_mfma_f32_16x16x32_bf16 v[28:31], v[166:169], v[212:215], v[28:31]
	v_mfma_f32_16x16x32_bf16 v[20:23], v[158:161], v[230:233], v[20:23]
	v_mfma_f32_16x16x32_bf16 v[12:15], v[166:169], v[230:233], v[12:15]
	v_mfma_f32_16x16x32_bf16 v[52:55], v[170:173], v[192:195], v[52:55]
	v_mfma_f32_16x16x32_bf16 v[44:47], v[178:181], v[192:195], v[44:47]
	v_mfma_f32_16x16x32_bf16 v[32:35], v[170:173], v[200:203], v[32:35]
	v_mfma_f32_16x16x32_bf16 v[24:27], v[178:181], v[200:203], v[24:27]
	v_mfma_f32_16x16x32_bf16 v[16:19], v[170:173], v[208:211], v[16:19]
	v_mfma_f32_16x16x32_bf16 v[8:11], v[178:181], v[208:211], v[8:11]
	v_mfma_f32_16x16x32_bf16 v[4:7], v[170:173], v[216:219], v[4:7]
	v_mfma_f32_16x16x32_bf16 v[0:3], v[178:181], v[216:219], v[0:3]
	v_mfma_f32_16x16x32_bf16 v[52:55], v[174:177], v[196:199], v[52:55]
	v_mfma_f32_16x16x32_bf16 v[44:47], v[188:191], v[196:199], v[44:47]
	v_mfma_f32_16x16x32_bf16 v[32:35], v[174:177], v[204:207], v[32:35]
	v_mfma_f32_16x16x32_bf16 v[24:27], v[188:191], v[204:207], v[24:27]
	v_mfma_f32_16x16x32_bf16 v[16:19], v[174:177], v[212:215], v[16:19]
	v_mfma_f32_16x16x32_bf16 v[8:11], v[188:191], v[212:215], v[8:11]
	v_mfma_f32_16x16x32_bf16 v[4:7], v[174:177], v[230:233], v[4:7]
	v_mfma_f32_16x16x32_bf16 v[0:3], v[188:191], v[230:233], v[0:3]
	s_barrier
	s_add_i32 s46, s46, 2
	s_add_u32 s16, s16, 0x100
	s_addc_u32 s17, s17, 0
	s_add_u32 s44, s44, 0x100
	s_addc_u32 s45, s45, 0
	s_cmp_gt_u32 s46, 13

; #define PG8_STAGE(bufoff, gbase, voff) do { _Pragma("unroll") for (int _i = 0; _i < 2; ++_i) \
;         __builtin_amdgcn_global_load_lds((const unsigned*)((const char*)(gbase) + (voff)[_i]), (PG8_LAS unsigned*)(lds + (bufoff) + ldsw + _i * 8192), 16, 0, 0); } while (0)
; #define PG8_LDA(dst, b, h) do { _Pragma("unroll") for (int m = 0; m < 4; ++m) _Pragma("unroll") for (int k = 0; k < 2; ++k) dst[m][k] = *(const PG8_LAS bf16x8*)(lds + PG8_SA(b, h) + aoff + m * 2048 + k * 1024); } while (0)
; #define PG8_LDB(dst, b, h) do { _Pragma("unroll") for (int n = 0; n < 2; ++n) _Pragma("unroll") for (int k = 0; k < 2; ++k) dst[n][k] = *(const PG8_LAS bf16x8*)(lds + PG8_SB(b, h) + boff + n * 2048 + k * 1024); } while (0)
; #define PG8_MMA(ai, bj, At, Bt) do { __builtin_amdgcn_s_setprio(1); _Pragma("unroll") for (int m = 0; m < 4; ++m) _Pragma("unroll") for (int n = 0; n < 2; ++n) _Pragma("unroll") for (int k = 0; k < 2; ++k) \
;         acc[ai][bj][m][n] = __builtin_amdgcn_mfma_f32_16x16x32_bf16(Bt[n][k], At[m][k], acc[ai][bj][m][n], 0, 0, 0); __builtin_amdgcn_s_setprio(0); } while (0)
; #define PG8_WAIT_V(n) asm volatile("s_waitcnt vmcnt(" #n ")" ::: "memory")
; #define PG8_WAIT_L(n) asm volatile("s_waitcnt lgkmcnt(" #n ")" ::: "memory")
; #define PG8_BAR __builtin_amdgcn_s_barrier()
; #define PG8_SCHED __builtin_amdgcn_sched_barrier(0)
; template <class Epi, class Sched, bool ALIGN_EPI = false, bool SP2 = false>
; __device__ __forceinline__ void gemm_phase(PG8_LAS unsigned char* lds, const Gemm g, const Sched& S, const Epi& E) {
;     ...
;             PG8_LDB(B0, 0, 0); PG8_LDB(B1, 0, 1); PG8_SCHED; PG8_LDA(At, 0, 0); PG8_STAGE(PG8_SA(1, 1), a1 + hstep, voffA);
;             PG8_WAIT_V(8); PG8_WAIT_L(0); PG8_BAR; PG8_MMA(0, 0, At, B0); PG8_MMA(0, 1, At, B1); PG8_BAR; PG8_SCHED;
;             PG8_LDA(At, 0, 1); PG8_STAGE(PG8_SB(0, 0), b2, voffB); PG8_STAGE(PG8_SB(0, 1), b2 + hstep, voffB); PG8_STAGE(PG8_SA(0, 0), a2, voffA);
;     ...
;         for (int a = 0; a < 2; ++a)
; #pragma unroll
;             for (int b = 0; b < 2; ++b)
; #pragma unroll
;                 for (int m = 0; m < 4; ++m)
; #pragma unroll
;                     for (int n = 0; n < 2; ++n) acc[a][b][m][n] = (f32x4){0.f, 0.f, 0.f, 0.f};
.LBB0_472:
	s_ashr_i32 s55, s54, 31
	s_lshl_b64 s[10:11], s[54:55], 19
	s_add_u32 s56, s66, s10
	s_addc_u32 s57, s67, s11
	s_and_b64 s[10:11], s[60:61], exec
	s_cselect_b32 s5, s57, s7
	s_cselect_b32 s24, s56, s6
	s_ashr_i32 s53, s52, 31
	s_lshl_b64 s[10:11], s[52:53], 19
	s_add_u32 s58, s13, s10
	s_addc_u32 s59, s14, s11
	s_and_b64 s[10:11], s[60:61], exec
	s_cselect_b32 s25, s59, s9
	s_cselect_b32 s26, s58, s8
	s_add_u32 s6, s6, 0x40080
	s_addc_u32 s7, s7, 0
	s_add_u32 s27, s8, 0x100
	s_addc_u32 s28, s9, 0
	s_mov_b32 s29, -2
	s_mov_b64 s[40:41], 0x80
	s_add_u32 s8, s6, 0xfffc0080
	s_addc_u32 s9, s7, -1
	s_add_i32 s33, 0, 0x10000
	s_cmp_eq_u32 s29, 12
	s_cselect_b32 s11, s5, s9
	s_cselect_b32 s10, s24, s8
	v_add_u32_e32 v64, s33, v161
	s_cselect_b32 s9, s25, s28
	s_cselect_b32 s8, s26, s27
	s_add_i32 s36, 0, 0x14000
	ds_read_b128 v[130:133], v64
	ds_read_b128 v[134:137], v64 offset:1024
	ds_read_b128 v[138:141], v64 offset:2048
	ds_read_b128 v[142:145], v64 offset:3072
	v_add_u32_e32 v64, s36, v161
	ds_read_b128 v[166:169], v64
	ds_read_b128 v[170:173], v64 offset:1024
	ds_read_b128 v[174:177], v64 offset:2048
	ds_read_b128 v[178:181], v64 offset:3072
	v_lshl_add_u64 v[158:159], s[6:7], 0, v[154:155]
	s_add_i32 m0, s16, 0xc000
	ds_read_b128 v[188:191], v164
	ds_read_b128 v[192:195], v164 offset:1024
	ds_read_b128 v[196:199], v164 offset:2048
	ds_read_b128 v[200:203], v164 offset:3072
	ds_read_b128 v[204:207], v164 offset:4096
	ds_read_b128 v[208:211], v164 offset:5120
	ds_read_b128 v[212:215], v164 offset:6144
	ds_read_b128 v[216:219], v164 offset:7168
	global_load_lds_dwordx4 v[158:159], off
	v_lshl_add_u64 v[158:159], s[6:7], 0, v[156:157]
	s_add_i32 m0, s16, 0xe000
	s_nop 0
	global_load_lds_dwordx4 v[158:159], off
	s_waitcnt vmcnt(8)
	s_waitcnt lgkmcnt(0)
	s_barrier
	v_mfma_f32_16x16x32_bf16 v[126:129], v[130:133], v[188:191], 0
	v_mfma_f32_16x16x32_bf16 v[122:125], v[138:141], v[188:191], 0
	v_mfma_f32_16x16x32_bf16 v[110:113], v[130:133], v[196:199], 0
	v_mfma_f32_16x16x32_bf16 v[106:109], v[138:141], v[196:199], 0
	v_mfma_f32_16x16x32_bf16 v[94:97], v[130:133], v[204:207], 0
	v_mfma_f32_16x16x32_bf16 v[90:93], v[138:141], v[204:207], 0
	v_mfma_f32_16x16x32_bf16 v[78:81], v[130:133], v[212:215], 0
	v_mfma_f32_16x16x32_bf16 v[74:77], v[138:141], v[212:215], 0
	v_mfma_f32_16x16x32_bf16 v[126:129], v[134:137], v[192:195], v[126:129]
	v_mfma_f32_16x16x32_bf16 v[122:125], v[142:145], v[192:195], v[122:125]
	v_mfma_f32_16x16x32_bf16 v[110:113], v[134:137], v[200:203], v[110:113]
	v_mfma_f32_16x16x32_bf16 v[106:109], v[142:145], v[200:203], v[106:109]
	v_mfma_f32_16x16x32_bf16 v[94:97], v[134:137], v[208:211], v[94:97]
	v_mfma_f32_16x16x32_bf16 v[90:93], v[142:145], v[208:211], v[90:93]
	v_mfma_f32_16x16x32_bf16 v[78:81], v[134:137], v[216:219], v[78:81]
	v_mfma_f32_16x16x32_bf16 v[74:77], v[142:145], v[216:219], v[74:77]
	v_mfma_f32_16x16x32_bf16 v[118:121], v[166:169], v[188:191], 0
	v_mfma_f32_16x16x32_bf16 v[114:117], v[174:177], v[188:191], 0
	v_mfma_f32_16x16x32_bf16 v[102:105], v[166:169], v[196:199], 0
	v_mfma_f32_16x16x32_bf16 v[98:101], v[174:177], v[196:199], 0
	v_mfma_f32_16x16x32_bf16 v[86:89], v[166:169], v[204:207], 0
	v_mfma_f32_16x16x32_bf16 v[82:85], v[174:177], v[204:207], 0
	v_mfma_f32_16x16x32_bf16 v[70:73], v[166:169], v[212:215], 0
	v_mfma_f32_16x16x32_bf16 v[66:69], v[174:177], v[212:215], 0
	v_mfma_f32_16x16x32_bf16 v[118:121], v[170:173], v[192:195], v[118:121]
	v_mfma_f32_16x16x32_bf16 v[114:117], v[178:181], v[192:195], v[114:117]
	v_mfma_f32_16x16x32_bf16 v[102:105], v[170:173], v[200:203], v[102:105]
	v_mfma_f32_16x16x32_bf16 v[98:101], v[178:181], v[200:203], v[98:101]
	v_mfma_f32_16x16x32_bf16 v[86:89], v[170:173], v[208:211], v[86:89]
	v_mfma_f32_16x16x32_bf16 v[82:85], v[178:181], v[208:211], v[82:85]
	v_mfma_f32_16x16x32_bf16 v[70:73], v[170:173], v[216:219], v[70:73]
	v_mfma_f32_16x16x32_bf16 v[66:69], v[178:181], v[216:219], v[66:69]
	s_barrier
	s_add_i32 s33, s33, s15
	v_lshl_add_u64 v[158:159], s[8:9], 0, v[148:149]
	s_mov_b32 m0, s33
	ds_read_b128 v[188:191], v164 offset:16384
	ds_read_b128 v[192:195], v164 offset:17408
	ds_read_b128 v[196:199], v164 offset:18432
	ds_read_b128 v[200:203], v164 offset:19456
	ds_read_b128 v[204:207], v164 offset:20480
	ds_read_b128 v[208:211], v164 offset:21504
	ds_read_b128 v[212:215], v164 offset:22528
	ds_read_b128 v[216:219], v164 offset:23552
	global_load_lds_dwordx4 v[158:159], off
	s_add_i32 m0, s33, 0x2000
	s_add_u32 s34, s8, 0x40000
	v_lshl_add_u64 v[182:183], s[8:9], 0, v[152:153]
	s_addc_u32 s35, s9, 0
	s_add_i32 s33, s36, s15
	global_load_lds_dwordx4 v[182:183], off
	v_lshl_add_u64 v[230:231], s[34:35], 0, v[148:149]
	s_mov_b32 m0, s33
	v_lshl_add_u64 v[232:233], s[10:11], 0, v[150:151]
	global_load_lds_dwordx4 v[230:231], off
	v_lshl_add_u64 v[230:231], s[34:35], 0, v[152:153]
	s_add_i32 m0, s33, 0x2000
	s_nop 0
	global_load_lds_dwordx4 v[230:231], off
	v_lshl_add_u64 v[230:231], s[10:11], 0, v[146:147]
	s_mov_b32 m0, s16
	s_nop 0
	global_load_lds_dwordx4 v[230:231], off
	s_mov_b32 m0, s17
	s_nop 0
	global_load_lds_dwordx4 v[232:233], off
	s_waitcnt vmcnt(8)
	s_waitcnt lgkmcnt(0)
	s_barrier
; #define PG8_STAGE(bufoff, gbase, voff) do { _Pragma("unroll") for (int _i = 0; _i < 2; ++_i) \
;         __builtin_amdgcn_global_load_lds((const unsigned*)((const char*)(gbase) + (voff)[_i]), (PG8_LAS unsigned*)(lds + (bufoff) + ldsw + _i * 8192), 16, 0, 0); } while (0)
; #define PG8_LDA(dst, b, h) do { _Pragma("unroll") for (int m = 0; m < 4; ++m) _Pragma("unroll") for (int k = 0; k < 2; ++k) dst[m][k] = *(const PG8_LAS bf16x8*)(lds + PG8_SA(b, h) + aoff + m * 2048 + k * 1024); } while (0)
; #define PG8_LDB(dst, b, h) do { _Pragma("unroll") for (int n = 0; n < 2; ++n) _Pragma("unroll") for (int k = 0; k < 2; ++k) dst[n][k] = *(const PG8_LAS bf16x8*)(lds + PG8_SB(b, h) + boff + n * 2048 + k * 1024); } while (0)
; #define PG8_MMA(ai, bj, At, Bt) do { __builtin_amdgcn_s_setprio(1); _Pragma("unroll") for (int m = 0; m < 4; ++m) _Pragma("unroll") for (int n = 0; n < 2; ++n) _Pragma("unroll") for (int k = 0; k < 2; ++k) \
;         acc[ai][bj][m][n] = __builtin_amdgcn_mfma_f32_16x16x32_bf16(Bt[n][k], At[m][k], acc[ai][bj][m][n], 0, 0, 0); __builtin_amdgcn_s_setprio(0); } while (0)
; #define PG8_WAIT_V(n) asm volatile("s_waitcnt vmcnt(" #n ")" ::: "memory")
; #define PG8_WAIT_L(n) asm volatile("s_waitcnt lgkmcnt(" #n ")" ::: "memory")
; #define PG8_BAR __builtin_amdgcn_s_barrier()
; #define PG8_SCHED __builtin_amdgcn_sched_barrier(0)
; template <class Epi, class Sched, bool ALIGN_EPI = false, bool SP2 = false>
; __device__ __forceinline__ void gemm_phase(PG8_LAS unsigned char* lds, const Gemm g, const Sched& S, const Epi& E) {
;     ...
;             PG8_WAIT_V(8); PG8_WAIT_L(0); PG8_BAR; PG8_MMA(1, 0, At, B0); PG8_MMA(1, 1, At, B1); PG8_BAR; PG8_SCHED;
;             PG8_LDB(B0, 1, 0); PG8_LDB(B1, 1, 1); PG8_SCHED; PG8_LDA(At, 1, 0); PG8_STAGE(PG8_SA(0, 1), a2 + hstep, voffA);
;             PG8_WAIT_V(8); PG8_WAIT_L(0); PG8_BAR; PG8_MMA(0, 0, At, B0); PG8_MMA(0, 1, At, B1); PG8_BAR; PG8_SCHED;
	v_mfma_f32_16x16x32_bf16 v[60:63], v[130:133], v[188:191], 0
	v_mfma_f32_16x16x32_bf16 v[56:59], v[138:141], v[188:191], 0
	v_mfma_f32_16x16x32_bf16 v[44:47], v[130:133], v[196:199], 0
	v_mfma_f32_16x16x32_bf16 v[40:43], v[138:141], v[196:199], 0
	v_mfma_f32_16x16x32_bf16 v[28:31], v[130:133], v[204:207], 0
	v_mfma_f32_16x16x32_bf16 v[24:27], v[138:141], v[204:207], 0
	v_mfma_f32_16x16x32_bf16 v[12:15], v[130:133], v[212:215], 0
	v_mfma_f32_16x16x32_bf16 v[8:11], v[138:141], v[212:215], 0
	v_mfma_f32_16x16x32_bf16 v[60:63], v[134:137], v[192:195], v[60:63]
	v_mfma_f32_16x16x32_bf16 v[56:59], v[142:145], v[192:195], v[56:59]
	v_mfma_f32_16x16x32_bf16 v[44:47], v[134:137], v[200:203], v[44:47]
	v_mfma_f32_16x16x32_bf16 v[40:43], v[142:145], v[200:203], v[40:43]
	v_mfma_f32_16x16x32_bf16 v[28:31], v[134:137], v[208:211], v[28:31]
	v_mfma_f32_16x16x32_bf16 v[24:27], v[142:145], v[208:211], v[24:27]
	v_mfma_f32_16x16x32_bf16 v[12:15], v[134:137], v[216:219], v[12:15]
	v_mfma_f32_16x16x32_bf16 v[8:11], v[142:145], v[216:219], v[8:11]
	v_mfma_f32_16x16x32_bf16 v[52:55], v[166:169], v[188:191], 0
	v_mfma_f32_16x16x32_bf16 v[48:51], v[174:177], v[188:191], 0
	v_mfma_f32_16x16x32_bf16 v[36:39], v[166:169], v[196:199], 0
	v_mfma_f32_16x16x32_bf16 v[32:35], v[174:177], v[196:199], 0
	v_mfma_f32_16x16x32_bf16 v[20:23], v[166:169], v[204:207], 0
	v_mfma_f32_16x16x32_bf16 v[16:19], v[174:177], v[204:207], 0
	v_mfma_f32_16x16x32_bf16 v[4:7], v[166:169], v[212:215], 0
	v_mfma_f32_16x16x32_bf16 v[0:3], v[174:177], v[212:215], 0
	v_mfma_f32_16x16x32_bf16 v[52:55], v[170:173], v[192:195], v[52:55]
	v_mfma_f32_16x16x32_bf16 v[48:51], v[178:181], v[192:195], v[48:51]
	v_mfma_f32_16x16x32_bf16 v[36:39], v[170:173], v[200:203], v[36:39]
	v_mfma_f32_16x16x32_bf16 v[32:35], v[178:181], v[200:203], v[32:35]
	v_mfma_f32_16x16x32_bf16 v[20:23], v[170:173], v[208:211], v[20:23]
	v_mfma_f32_16x16x32_bf16 v[16:19], v[178:181], v[208:211], v[16:19]
	v_mfma_f32_16x16x32_bf16 v[4:7], v[170:173], v[216:219], v[4:7]
	v_mfma_f32_16x16x32_bf16 v[0:3], v[178:181], v[216:219], v[0:3]
	s_barrier
	s_add_i32 s33, 0, 0x18000
	v_add_u32_e32 v64, s33, v161
	s_add_i32 s34, 0, 0x1c000
	ds_read_b128 v[130:133], v64
	ds_read_b128 v[134:137], v64 offset:1024
	ds_read_b128 v[138:141], v64 offset:2048
	ds_read_b128 v[142:145], v64 offset:3072
	v_add_u32_e32 v64, s34, v161
	ds_read_b128 v[166:169], v64
	ds_read_b128 v[170:173], v64 offset:1024
	ds_read_b128 v[174:177], v64 offset:2048
	ds_read_b128 v[178:181], v64 offset:3072
	s_add_u32 s10, s10, 0x40000
	s_addc_u32 s11, s11, 0
	s_mov_b32 m0, s18
	v_lshl_add_u64 v[234:235], s[10:11], 0, v[146:147]
	ds_read_b128 v[188:191], v164 offset:32768
	ds_read_b128 v[192:195], v164 offset:33792
	ds_read_b128 v[196:199], v164 offset:34816
	ds_read_b128 v[200:203], v164 offset:35840
	ds_read_b128 v[204:207], v164 offset:36864
	ds_read_b128 v[208:211], v164 offset:37888
	ds_read_b128 v[212:215], v164 offset:38912
	ds_read_b128 v[216:219], v164 offset:39936
	global_load_lds_dwordx4 v[234:235], off
	v_lshl_add_u64 v[234:235], s[10:11], 0, v[150:151]
	s_mov_b32 m0, s19
	s_nop 0
	global_load_lds_dwordx4 v[234:235], off
	s_waitcnt vmcnt(8)
	s_waitcnt lgkmcnt(0)
	s_barrier
	v_mfma_f32_16x16x32_bf16 v[126:129], v[130:133], v[188:191], v[126:129]
	v_mfma_f32_16x16x32_bf16 v[122:125], v[138:141], v[188:191], v[122:125]
	v_mfma_f32_16x16x32_bf16 v[110:113], v[130:133], v[196:199], v[110:113]
	v_mfma_f32_16x16x32_bf16 v[106:109], v[138:141], v[196:199], v[106:109]
	v_mfma_f32_16x16x32_bf16 v[94:97], v[130:133], v[204:207], v[94:97]
	v_mfma_f32_16x16x32_bf16 v[90:93], v[138:141], v[204:207], v[90:93]
	v_mfma_f32_16x16x32_bf16 v[78:81], v[130:133], v[212:215], v[78:81]
	v_mfma_f32_16x16x32_bf16 v[74:77], v[138:141], v[212:215], v[74:77]
	v_mfma_f32_16x16x32_bf16 v[126:129], v[134:137], v[192:195], v[126:129]
	v_mfma_f32_16x16x32_bf16 v[122:125], v[142:145], v[192:195], v[122:125]
	v_mfma_f32_16x16x32_bf16 v[110:113], v[134:137], v[200:203], v[110:113]
	v_mfma_f32_16x16x32_bf16 v[106:109], v[142:145], v[200:203], v[106:109]
	v_mfma_f32_16x16x32_bf16 v[94:97], v[134:137], v[208:211], v[94:97]
	v_mfma_f32_16x16x32_bf16 v[90:93], v[142:145], v[208:211], v[90:93]
	v_mfma_f32_16x16x32_bf16 v[78:81], v[134:137], v[216:219], v[78:81]
	v_mfma_f32_16x16x32_bf16 v[74:77], v[142:145], v[216:219], v[74:77]
	v_mfma_f32_16x16x32_bf16 v[118:121], v[166:169], v[188:191], v[118:121]
	v_mfma_f32_16x16x32_bf16 v[114:117], v[174:177], v[188:191], v[114:117]
	v_mfma_f32_16x16x32_bf16 v[102:105], v[166:169], v[196:199], v[102:105]
	v_mfma_f32_16x16x32_bf16 v[98:101], v[174:177], v[196:199], v[98:101]
	v_mfma_f32_16x16x32_bf16 v[86:89], v[166:169], v[204:207], v[86:89]
	v_mfma_f32_16x16x32_bf16 v[82:85], v[174:177], v[204:207], v[82:85]
	v_mfma_f32_16x16x32_bf16 v[70:73], v[166:169], v[212:215], v[70:73]
	v_mfma_f32_16x16x32_bf16 v[66:69], v[174:177], v[212:215], v[66:69]
	v_mfma_f32_16x16x32_bf16 v[118:121], v[170:173], v[192:195], v[118:121]
	v_mfma_f32_16x16x32_bf16 v[114:117], v[178:181], v[192:195], v[114:117]
	v_mfma_f32_16x16x32_bf16 v[102:105], v[170:173], v[200:203], v[102:105]
	v_mfma_f32_16x16x32_bf16 v[98:101], v[178:181], v[200:203], v[98:101]
	v_mfma_f32_16x16x32_bf16 v[86:89], v[170:173], v[208:211], v[86:89]
	v_mfma_f32_16x16x32_bf16 v[82:85], v[178:181], v[208:211], v[82:85]
	v_mfma_f32_16x16x32_bf16 v[70:73], v[170:173], v[216:219], v[70:73]
	v_mfma_f32_16x16x32_bf16 v[66:69], v[178:181], v[216:219], v[66:69]
	s_barrier
; #define PG8_STAGE(bufoff, gbase, voff) do { _Pragma("unroll") for (int _i = 0; _i < 2; ++_i) \
;         __builtin_amdgcn_global_load_lds((const unsigned*)((const char*)(gbase) + (voff)[_i]), (PG8_LAS unsigned*)(lds + (bufoff) + ldsw + _i * 8192), 16, 0, 0); } while (0)
; #define PG8_LDA(dst, b, h) do { _Pragma("unroll") for (int m = 0; m < 4; ++m) _Pragma("unroll") for (int k = 0; k < 2; ++k) dst[m][k] = *(const PG8_LAS bf16x8*)(lds + PG8_SA(b, h) + aoff + m * 2048 + k * 1024); } while (0)
; #define PG8_MMA(ai, bj, At, Bt) do { __builtin_amdgcn_s_setprio(1); _Pragma("unroll") for (int m = 0; m < 4; ++m) _Pragma("unroll") for (int n = 0; n < 2; ++n) _Pragma("unroll") for (int k = 0; k < 2; ++k) \
;         acc[ai][bj][m][n] = __builtin_amdgcn_mfma_f32_16x16x32_bf16(Bt[n][k], At[m][k], acc[ai][bj][m][n], 0, 0, 0); __builtin_amdgcn_s_setprio(0); } while (0)
; #define PG8_WAIT_V(n) asm volatile("s_waitcnt vmcnt(" #n ")" ::: "memory")
; #define PG8_WAIT_L(n) asm volatile("s_waitcnt lgkmcnt(" #n ")" ::: "memory")
; #define PG8_BAR __builtin_amdgcn_s_barrier()
; #define PG8_SCHED __builtin_amdgcn_sched_barrier(0)
; template <class Epi, class Sched, bool ALIGN_EPI = false, bool SP2 = false>
; __device__ __forceinline__ void gemm_phase(PG8_LAS unsigned char* lds, const Gemm g, const Sched& S, const Epi& E) {
;     ...
;             PG8_LDA(At, 1, 1); PG8_STAGE(PG8_SB(1, 0), b3, voffB); PG8_STAGE(PG8_SB(1, 1), b3 + hstep, voffB); PG8_STAGE(PG8_SA(1, 0), a3, voffA);
;             PG8_WAIT_V(8); PG8_WAIT_L(0); PG8_BAR; PG8_MMA(1, 0, At, B0); PG8_MMA(1, 1, At, B1); PG8_BAR; PG8_SCHED;
	s_add_i32 s10, s33, s15
	v_lshl_add_u64 v[158:159], v[158:159], 0, s[40:41]
	s_mov_b32 m0, s10
	ds_read_b128 v[188:191], v164 offset:49152
	ds_read_b128 v[192:195], v164 offset:50176
	ds_read_b128 v[196:199], v164 offset:51200
	ds_read_b128 v[200:203], v164 offset:52224
	ds_read_b128 v[204:207], v164 offset:53248
	ds_read_b128 v[208:211], v164 offset:54272
	ds_read_b128 v[212:215], v164 offset:55296
	ds_read_b128 v[216:219], v164 offset:56320
	global_load_lds_dwordx4 v[158:159], off
	s_add_i32 m0, s10, 0x2000
	s_add_u32 s8, s8, 0x40080
	v_lshl_add_u64 v[158:159], v[182:183], 0, s[40:41]
	s_addc_u32 s9, s9, 0
	s_add_i32 s10, s34, s15
	global_load_lds_dwordx4 v[158:159], off
	v_lshl_add_u64 v[158:159], s[8:9], 0, v[148:149]
	s_mov_b32 m0, s10
	s_nop 0
	global_load_lds_dwordx4 v[158:159], off
	v_lshl_add_u64 v[158:159], s[8:9], 0, v[152:153]
	s_add_i32 m0, s10, 0x2000
	s_nop 0
	global_load_lds_dwordx4 v[158:159], off
	v_lshl_add_u64 v[158:159], v[230:231], 0, s[40:41]
	s_mov_b32 m0, s20
	s_nop 0
	global_load_lds_dwordx4 v[158:159], off
	v_lshl_add_u64 v[158:159], v[232:233], 0, s[40:41]
	s_mov_b32 m0, s21
	s_nop 0
	global_load_lds_dwordx4 v[158:159], off
	s_waitcnt vmcnt(8)
	s_waitcnt lgkmcnt(0)
	s_barrier
	v_mfma_f32_16x16x32_bf16 v[60:63], v[130:133], v[188:191], v[60:63]
	v_mfma_f32_16x16x32_bf16 v[56:59], v[138:141], v[188:191], v[56:59]
	v_mfma_f32_16x16x32_bf16 v[44:47], v[130:133], v[196:199], v[44:47]
	v_mfma_f32_16x16x32_bf16 v[40:43], v[138:141], v[196:199], v[40:43]
	v_mfma_f32_16x16x32_bf16 v[28:31], v[130:133], v[204:207], v[28:31]
	v_mfma_f32_16x16x32_bf16 v[24:27], v[138:141], v[204:207], v[24:27]
	v_mfma_f32_16x16x32_bf16 v[12:15], v[130:133], v[212:215], v[12:15]
	v_mfma_f32_16x16x32_bf16 v[8:11], v[138:141], v[212:215], v[8:11]
	v_mfma_f32_16x16x32_bf16 v[60:63], v[134:137], v[192:195], v[60:63]
	v_mfma_f32_16x16x32_bf16 v[56:59], v[142:145], v[192:195], v[56:59]
	v_mfma_f32_16x16x32_bf16 v[44:47], v[134:137], v[200:203], v[44:47]
	v_mfma_f32_16x16x32_bf16 v[40:43], v[142:145], v[200:203], v[40:43]
	v_mfma_f32_16x16x32_bf16 v[28:31], v[134:137], v[208:211], v[28:31]
	v_mfma_f32_16x16x32_bf16 v[24:27], v[142:145], v[208:211], v[24:27]
	v_mfma_f32_16x16x32_bf16 v[12:15], v[134:137], v[216:219], v[12:15]
	v_mfma_f32_16x16x32_bf16 v[8:11], v[142:145], v[216:219], v[8:11]
	v_mfma_f32_16x16x32_bf16 v[52:55], v[166:169], v[188:191], v[52:55]
	v_mfma_f32_16x16x32_bf16 v[48:51], v[174:177], v[188:191], v[48:51]
	v_mfma_f32_16x16x32_bf16 v[36:39], v[166:169], v[196:199], v[36:39]
	v_mfma_f32_16x16x32_bf16 v[32:35], v[174:177], v[196:199], v[32:35]
	v_mfma_f32_16x16x32_bf16 v[20:23], v[166:169], v[204:207], v[20:23]
	v_mfma_f32_16x16x32_bf16 v[16:19], v[174:177], v[204:207], v[16:19]
	v_mfma_f32_16x16x32_bf16 v[4:7], v[166:169], v[212:215], v[4:7]
	v_mfma_f32_16x16x32_bf16 v[0:3], v[174:177], v[212:215], v[0:3]
	v_mfma_f32_16x16x32_bf16 v[52:55], v[170:173], v[192:195], v[52:55]
	v_mfma_f32_16x16x32_bf16 v[48:51], v[178:181], v[192:195], v[48:51]
	v_mfma_f32_16x16x32_bf16 v[36:39], v[170:173], v[200:203], v[36:39]
	v_mfma_f32_16x16x32_bf16 v[32:35], v[178:181], v[200:203], v[32:35]
	v_mfma_f32_16x16x32_bf16 v[20:23], v[170:173], v[208:211], v[20:23]
	v_mfma_f32_16x16x32_bf16 v[16:19], v[178:181], v[208:211], v[16:19]
	v_mfma_f32_16x16x32_bf16 v[4:7], v[170:173], v[216:219], v[4:7]
	v_mfma_f32_16x16x32_bf16 v[0:3], v[178:181], v[216:219], v[0:3]
	s_barrier
	s_add_i32 s29, s29, 2
	s_add_u32 s6, s6, 0x100
	s_addc_u32 s7, s7, 0
	s_add_u32 s27, s27, 0x100
	s_addc_u32 s28, s28, 0
	s_cmp_gt_u32 s29, 13
